# merge branch epilogue de-serialised: scratch-gate and old-merged loads pipelined 7 deep with counted vmcnt
# speedup vs baseline: 1.0069x; 1.0069x over previous
.Ltail_92:
	s_add_i32 s20, s20, 1
	s_cmp_lg_u32 s20, s17
	s_cbranch_scc1 .LBB0_78
	v_mov_b32_e32 v192, v222
	s_bitcmp1_b32 s18, 0
	s_cselect_b64 s[12:13], -1, 0
	v_ashrrev_i32_e32 v193, 31, v192
	v_lshl_add_u64 v[190:191], v[192:193], 2, s[6:7]
	s_mov_b64 s[4:5], -1
	s_and_b64 vcc, exec, s[12:13]
	s_cbranch_vccz .LBB0_159
	s_mov_b64 s[98:99], 0x1000
	global_load_dword v198, v[190:191], off
	global_load_dword v199, v[190:191], off offset:1024
	global_load_dword v202, v[190:191], off offset:2048
	global_load_dword v203, v[190:191], off offset:3072
	v_lshl_add_u64 v[190:191], v[190:191], 0, s[98:99]
	global_load_dword v206, v[190:191], off
	global_load_dword v207, v[190:191], off offset:1024
	global_load_dword v216, v[190:191], off offset:2048
	global_load_dword v217, v[190:191], off offset:3072
	v_lshl_add_u64 v[190:191], v[190:191], 0, s[98:99]
	global_load_dword v236, v[190:191], off
	global_load_dword v237, v[190:191], off offset:1024
	global_load_dword v240, v[190:191], off offset:2048
	global_load_dword v241, v[190:191], off offset:3072
	v_lshl_add_u64 v[190:191], v[190:191], 0, s[98:99]
	global_load_dword v244, v[190:191], off
	global_load_dword v245, v[190:191], off offset:1024
	s_ashr_i32 s4, s18, 3
	s_mul_i32 s4, s4, s82
	s_add_i32 s4, s4, s63
	s_ashr_i32 s5, s4, 31
	s_lshr_b32 s5, s5, 28
	s_add_i32 s5, s4, s5
	s_ashr_i32 s12, s5, 4
	s_and_b32 s5, s5, -16
	s_sub_i32 s13, s4, s5
	s_lshl_b32 s4, s12, 1
	s_and_b32 s5, s13, 1
	s_or_b32 s12, s5, s4
	v_readlane_b32 s4, v252, 35
	s_and_b32 s9, s18, 7
	s_sub_i32 s15, 0x7f, s12
	v_readlane_b32 s5, v252, 36
	s_and_b64 s[4:5], s[4:5], exec
	s_cselect_b32 s4, s15, s12
	s_ashr_i32 s5, s4, 31
	v_and_b32_e32 v194, 0xffffff80, v192
	s_lshl_b64 s[4:5], s[4:5], 8
	v_ashrrev_i32_e32 v195, 31, v194
	v_lshl_add_u64 v[194:195], s[4:5], 0, v[194:195]
	v_lshrrev_b32_e32 v179, 3, v192
	v_and_or_b32 v194, v192, 31, v194
	v_and_b32_e32 v179, 4, v179
	v_and_b32_e32 v0, 64, v192
	v_lshlrev_b64 v[192:193], 11, v[194:195]
	v_lshlrev_b32_e32 v194, 1, v179
	s_lshl_b32 s4, s13, 6
	s_and_b32 s4, s4, 0xffffff80
	s_ashr_i32 s5, s4, 31
	v_lshl_add_u64 v[192:193], s[2:3], 0, v[192:193]
	v_lshl_add_u64 v[192:193], s[4:5], 1, v[192:193]
	v_lshlrev_b32_e32 v0, 1, v0
	s_cmp_lg_u32 s9, 1
	v_lshl_add_u64 v[196:197], v[192:193], 0, v[0:1]
	v_mov_b32_e32 v195, v1
	s_cselect_b64 s[12:13], -1, 0
	s_cmp_eq_u32 s9, 1
	v_lshl_add_u64 v[196:197], v[196:197], 0, v[194:195]
	v_lshl_add_u64 v[192:193], v[196:197], 0, 0
	s_cbranch_scc1 .Lme_noold
	global_load_dwordx2 v[200:201], v[192:193], off
	global_load_dwordx2 v[204:205], v[192:193], off offset:16
	global_load_dwordx2 v[208:209], v[192:193], off offset:32
	global_load_dwordx2 v[218:219], v[192:193], off offset:48
	global_load_dwordx2 v[238:239], v[192:193], off offset:64
	global_load_dwordx2 v[242:243], v[192:193], off offset:80
	global_load_dwordx2 v[246:247], v[192:193], off offset:96
	s_waitcnt vmcnt(6)
	v_lshlrev_b32_e32 v194, 16, v198
	v_and_b32_e32 v195, 0xffff0000, v198
	v_lshlrev_b32_e32 v220, 16, v199
	v_and_b32_e32 v221, 0xffff0000, v199
	v_pk_mul_f32 v[194:195], v[114:115], v[194:195]
	v_pk_mul_f32 v[220:221], v[116:117], v[220:221]
	v_lshlrev_b32_e32 v198, 16, v200
	v_and_b32_e32 v199, 0xffff0000, v200
	v_lshlrev_b32_e32 v200, 16, v201
	v_and_b32_e32 v201, 0xffff0000, v201
	v_pk_add_f32 v[194:195], v[194:195], v[198:199]
	v_pk_add_f32 v[220:221], v[220:221], v[200:201]
	v_cvt_pk_bf16_f32 v198, v194, v195
	v_cvt_pk_bf16_f32 v199, v220, v221
	global_store_dwordx2 v[196:197], v[198:199], off
	global_load_dword v198, v[190:191], off offset:2048
	global_load_dword v199, v[190:191], off offset:3072
	global_load_dwordx2 v[200:201], v[192:193], off offset:112
	s_waitcnt vmcnt(9)
	v_lshlrev_b32_e32 v194, 16, v202
	v_and_b32_e32 v195, 0xffff0000, v202
	v_lshlrev_b32_e32 v220, 16, v203
	v_and_b32_e32 v221, 0xffff0000, v203
	v_pk_mul_f32 v[194:195], v[118:119], v[194:195]
	v_pk_mul_f32 v[220:221], v[120:121], v[220:221]
	v_lshlrev_b32_e32 v202, 16, v204
	v_and_b32_e32 v203, 0xffff0000, v204
	v_lshlrev_b32_e32 v204, 16, v205
	v_and_b32_e32 v205, 0xffff0000, v205
	v_pk_add_f32 v[194:195], v[194:195], v[202:203]
	v_pk_add_f32 v[220:221], v[220:221], v[204:205]
	v_cvt_pk_bf16_f32 v202, v194, v195
	v_cvt_pk_bf16_f32 v203, v220, v221
	global_store_dwordx2 v[196:197], v[202:203], off offset:16
	v_lshl_add_u64 v[190:191], v[190:191], 0, s[98:99]
	global_load_dword v202, v[190:191], off
	global_load_dword v203, v[190:191], off offset:1024
	v_lshl_add_u64 v[192:193], v[192:193], 0, s[90:91]
	global_load_dwordx2 v[204:205], v[192:193], off
	s_waitcnt vmcnt(12)
	v_lshlrev_b32_e32 v194, 16, v206
	v_and_b32_e32 v195, 0xffff0000, v206
	v_lshlrev_b32_e32 v220, 16, v207
	v_and_b32_e32 v221, 0xffff0000, v207
	v_pk_mul_f32 v[194:195], v[122:123], v[194:195]
	v_pk_mul_f32 v[220:221], v[124:125], v[220:221]
	v_lshlrev_b32_e32 v206, 16, v208
	v_and_b32_e32 v207, 0xffff0000, v208
	v_lshlrev_b32_e32 v208, 16, v209
	v_and_b32_e32 v209, 0xffff0000, v209
	v_pk_add_f32 v[194:195], v[194:195], v[206:207]
	v_pk_add_f32 v[220:221], v[220:221], v[208:209]
	v_cvt_pk_bf16_f32 v206, v194, v195
	v_cvt_pk_bf16_f32 v207, v220, v221
	global_store_dwordx2 v[196:197], v[206:207], off offset:32
	global_load_dword v206, v[190:191], off offset:2048
	global_load_dword v207, v[190:191], off offset:3072
	global_load_dwordx2 v[208:209], v[192:193], off offset:16
	s_waitcnt vmcnt(15)
	v_lshlrev_b32_e32 v194, 16, v216
	v_and_b32_e32 v195, 0xffff0000, v216
	v_lshlrev_b32_e32 v220, 16, v217
	v_and_b32_e32 v221, 0xffff0000, v217
	v_pk_mul_f32 v[194:195], v[126:127], v[194:195]
	v_pk_mul_f32 v[220:221], v[128:129], v[220:221]
	v_lshlrev_b32_e32 v216, 16, v218
	v_and_b32_e32 v217, 0xffff0000, v218
	v_lshlrev_b32_e32 v218, 16, v219
	v_and_b32_e32 v219, 0xffff0000, v219
	v_pk_add_f32 v[194:195], v[194:195], v[216:217]
	v_pk_add_f32 v[220:221], v[220:221], v[218:219]
	v_cvt_pk_bf16_f32 v216, v194, v195
	v_cvt_pk_bf16_f32 v217, v220, v221
	global_store_dwordx2 v[196:197], v[216:217], off offset:48
	v_lshl_add_u64 v[190:191], v[190:191], 0, s[98:99]
	global_load_dword v216, v[190:191], off
	global_load_dword v217, v[190:191], off offset:1024
	global_load_dwordx2 v[218:219], v[192:193], off offset:32
	s_waitcnt vmcnt(18)
	v_lshlrev_b32_e32 v194, 16, v236
	v_and_b32_e32 v195, 0xffff0000, v236
	v_lshlrev_b32_e32 v220, 16, v237
	v_and_b32_e32 v221, 0xffff0000, v237
	v_pk_mul_f32 v[194:195], v[98:99], v[194:195]
	v_pk_mul_f32 v[220:221], v[100:101], v[220:221]
	v_lshlrev_b32_e32 v236, 16, v238
	v_and_b32_e32 v237, 0xffff0000, v238
	v_lshlrev_b32_e32 v238, 16, v239
	v_and_b32_e32 v239, 0xffff0000, v239
	v_pk_add_f32 v[194:195], v[194:195], v[236:237]
	v_pk_add_f32 v[220:221], v[220:221], v[238:239]
	v_cvt_pk_bf16_f32 v236, v194, v195
	v_cvt_pk_bf16_f32 v237, v220, v221
	global_store_dwordx2 v[196:197], v[236:237], off offset:64
	global_load_dword v236, v[190:191], off offset:2048
	global_load_dword v237, v[190:191], off offset:3072
	global_load_dwordx2 v[238:239], v[192:193], off offset:48
	s_waitcnt vmcnt(21)
	v_lshlrev_b32_e32 v194, 16, v240
	v_and_b32_e32 v195, 0xffff0000, v240
	v_lshlrev_b32_e32 v220, 16, v241
	v_and_b32_e32 v221, 0xffff0000, v241
	v_pk_mul_f32 v[194:195], v[102:103], v[194:195]
	v_pk_mul_f32 v[220:221], v[104:105], v[220:221]
	v_lshlrev_b32_e32 v240, 16, v242
	v_and_b32_e32 v241, 0xffff0000, v242
	v_lshlrev_b32_e32 v242, 16, v243
	v_and_b32_e32 v243, 0xffff0000, v243
	v_pk_add_f32 v[194:195], v[194:195], v[240:241]
	v_pk_add_f32 v[220:221], v[220:221], v[242:243]
	v_cvt_pk_bf16_f32 v240, v194, v195
	v_cvt_pk_bf16_f32 v241, v220, v221
	global_store_dwordx2 v[196:197], v[240:241], off offset:80
	v_lshl_add_u64 v[190:191], v[190:191], 0, s[98:99]
	global_load_dword v240, v[190:191], off
	global_load_dword v241, v[190:191], off offset:1024
	global_load_dwordx2 v[242:243], v[192:193], off offset:64
	s_waitcnt vmcnt(24)
	v_lshlrev_b32_e32 v194, 16, v244
	v_and_b32_e32 v195, 0xffff0000, v244
	v_lshlrev_b32_e32 v220, 16, v245
	v_and_b32_e32 v221, 0xffff0000, v245
	v_pk_mul_f32 v[194:195], v[106:107], v[194:195]
	v_pk_mul_f32 v[220:221], v[108:109], v[220:221]
	v_lshlrev_b32_e32 v244, 16, v246
	v_and_b32_e32 v245, 0xffff0000, v246
	v_lshlrev_b32_e32 v246, 16, v247
	v_and_b32_e32 v247, 0xffff0000, v247
	v_pk_add_f32 v[194:195], v[194:195], v[244:245]
	v_pk_add_f32 v[220:221], v[220:221], v[246:247]
	v_cvt_pk_bf16_f32 v244, v194, v195
	v_cvt_pk_bf16_f32 v245, v220, v221
	global_store_dwordx2 v[196:197], v[244:245], off offset:96
	global_load_dword v244, v[190:191], off offset:2048
	global_load_dword v245, v[190:191], off offset:3072
	global_load_dwordx2 v[246:247], v[192:193], off offset:80
	s_waitcnt vmcnt(24)
	v_lshlrev_b32_e32 v194, 16, v198
	v_and_b32_e32 v195, 0xffff0000, v198
	v_lshlrev_b32_e32 v220, 16, v199
	v_and_b32_e32 v221, 0xffff0000, v199
	v_pk_mul_f32 v[194:195], v[110:111], v[194:195]
	v_pk_mul_f32 v[220:221], v[112:113], v[220:221]
	v_lshlrev_b32_e32 v198, 16, v200
	v_and_b32_e32 v199, 0xffff0000, v200
	v_lshlrev_b32_e32 v200, 16, v201
	v_and_b32_e32 v201, 0xffff0000, v201
	v_pk_add_f32 v[194:195], v[194:195], v[198:199]
	v_pk_add_f32 v[220:221], v[220:221], v[200:201]
	v_cvt_pk_bf16_f32 v198, v194, v195
	v_cvt_pk_bf16_f32 v199, v220, v221
	global_store_dwordx2 v[196:197], v[198:199], off offset:112
	v_lshl_add_u64 v[190:191], v[190:191], 0, s[98:99]
	global_load_dword v198, v[190:191], off
	global_load_dword v199, v[190:191], off offset:1024
	global_load_dwordx2 v[200:201], v[192:193], off offset:96
	s_waitcnt vmcnt(24)
	v_lshlrev_b32_e32 v194, 16, v202
	v_and_b32_e32 v195, 0xffff0000, v202
	v_lshlrev_b32_e32 v220, 16, v203
	v_and_b32_e32 v221, 0xffff0000, v203
	v_pk_mul_f32 v[194:195], v[82:83], v[194:195]
	v_pk_mul_f32 v[220:221], v[84:85], v[220:221]
	v_lshlrev_b32_e32 v202, 16, v204
	v_and_b32_e32 v203, 0xffff0000, v204
	v_lshlrev_b32_e32 v204, 16, v205
	v_and_b32_e32 v205, 0xffff0000, v205
	v_pk_add_f32 v[194:195], v[194:195], v[202:203]
	v_pk_add_f32 v[220:221], v[220:221], v[204:205]
	v_cvt_pk_bf16_f32 v202, v194, v195
	v_cvt_pk_bf16_f32 v203, v220, v221
	v_lshl_add_u64 v[196:197], v[196:197], 0, s[90:91]
	global_store_dwordx2 v[196:197], v[202:203], off
	global_load_dword v202, v[190:191], off offset:2048
	global_load_dword v203, v[190:191], off offset:3072
	global_load_dwordx2 v[204:205], v[192:193], off offset:112
	s_waitcnt vmcnt(24)
	v_lshlrev_b32_e32 v194, 16, v206
	v_and_b32_e32 v195, 0xffff0000, v206
	v_lshlrev_b32_e32 v220, 16, v207
	v_and_b32_e32 v221, 0xffff0000, v207
	v_pk_mul_f32 v[194:195], v[86:87], v[194:195]
	v_pk_mul_f32 v[220:221], v[88:89], v[220:221]
	v_lshlrev_b32_e32 v206, 16, v208
	v_and_b32_e32 v207, 0xffff0000, v208
	v_lshlrev_b32_e32 v208, 16, v209
	v_and_b32_e32 v209, 0xffff0000, v209
	v_pk_add_f32 v[194:195], v[194:195], v[206:207]
	v_pk_add_f32 v[220:221], v[220:221], v[208:209]
	v_cvt_pk_bf16_f32 v206, v194, v195
	v_cvt_pk_bf16_f32 v207, v220, v221
	global_store_dwordx2 v[196:197], v[206:207], off offset:16
	v_lshl_add_u64 v[190:191], v[190:191], 0, s[98:99]
	global_load_dword v206, v[190:191], off
	global_load_dword v207, v[190:191], off offset:1024
	v_lshl_add_u64 v[192:193], v[192:193], 0, s[90:91]
	global_load_dwordx2 v[208:209], v[192:193], off
	s_waitcnt vmcnt(24)
	v_lshlrev_b32_e32 v194, 16, v216
	v_and_b32_e32 v195, 0xffff0000, v216
	v_lshlrev_b32_e32 v220, 16, v217
	v_and_b32_e32 v221, 0xffff0000, v217
	v_pk_mul_f32 v[194:195], v[90:91], v[194:195]
	v_pk_mul_f32 v[220:221], v[92:93], v[220:221]
	v_lshlrev_b32_e32 v216, 16, v218
	v_and_b32_e32 v217, 0xffff0000, v218
	v_lshlrev_b32_e32 v218, 16, v219
	v_and_b32_e32 v219, 0xffff0000, v219
	v_pk_add_f32 v[194:195], v[194:195], v[216:217]
	v_pk_add_f32 v[220:221], v[220:221], v[218:219]
	v_cvt_pk_bf16_f32 v216, v194, v195
	v_cvt_pk_bf16_f32 v217, v220, v221
	global_store_dwordx2 v[196:197], v[216:217], off offset:32
	global_load_dword v216, v[190:191], off offset:2048
	global_load_dword v217, v[190:191], off offset:3072
	global_load_dwordx2 v[218:219], v[192:193], off offset:16
	s_waitcnt vmcnt(24)
	v_lshlrev_b32_e32 v194, 16, v236
	v_and_b32_e32 v195, 0xffff0000, v236
	v_lshlrev_b32_e32 v220, 16, v237
	v_and_b32_e32 v221, 0xffff0000, v237
	v_pk_mul_f32 v[194:195], v[94:95], v[194:195]
	v_pk_mul_f32 v[220:221], v[96:97], v[220:221]
	v_lshlrev_b32_e32 v236, 16, v238
	v_and_b32_e32 v237, 0xffff0000, v238
	v_lshlrev_b32_e32 v238, 16, v239
	v_and_b32_e32 v239, 0xffff0000, v239
	v_pk_add_f32 v[194:195], v[194:195], v[236:237]
	v_pk_add_f32 v[220:221], v[220:221], v[238:239]
	v_cvt_pk_bf16_f32 v236, v194, v195
	v_cvt_pk_bf16_f32 v237, v220, v221
	global_store_dwordx2 v[196:197], v[236:237], off offset:48
	v_lshl_add_u64 v[190:191], v[190:191], 0, s[98:99]
	global_load_dword v236, v[190:191], off
	global_load_dword v237, v[190:191], off offset:1024
	global_load_dwordx2 v[238:239], v[192:193], off offset:32
	s_waitcnt vmcnt(24)
	v_lshlrev_b32_e32 v194, 16, v240
	v_and_b32_e32 v195, 0xffff0000, v240
	v_lshlrev_b32_e32 v220, 16, v241
	v_and_b32_e32 v221, 0xffff0000, v241
	v_pk_mul_f32 v[194:195], v[66:67], v[194:195]
	v_pk_mul_f32 v[220:221], v[68:69], v[220:221]
	v_lshlrev_b32_e32 v240, 16, v242
	v_and_b32_e32 v241, 0xffff0000, v242
	v_lshlrev_b32_e32 v242, 16, v243
	v_and_b32_e32 v243, 0xffff0000, v243
	v_pk_add_f32 v[194:195], v[194:195], v[240:241]
	v_pk_add_f32 v[220:221], v[220:221], v[242:243]
	v_cvt_pk_bf16_f32 v240, v194, v195
	v_cvt_pk_bf16_f32 v241, v220, v221
	global_store_dwordx2 v[196:197], v[240:241], off offset:64
	global_load_dword v240, v[190:191], off offset:2048
	global_load_dword v241, v[190:191], off offset:3072
	global_load_dwordx2 v[242:243], v[192:193], off offset:48
	s_waitcnt vmcnt(24)
	v_lshlrev_b32_e32 v194, 16, v244
	v_and_b32_e32 v195, 0xffff0000, v244
	v_lshlrev_b32_e32 v220, 16, v245
	v_and_b32_e32 v221, 0xffff0000, v245
	v_pk_mul_f32 v[194:195], v[70:71], v[194:195]
	v_pk_mul_f32 v[220:221], v[72:73], v[220:221]
	v_lshlrev_b32_e32 v244, 16, v246
	v_and_b32_e32 v245, 0xffff0000, v246
	v_lshlrev_b32_e32 v246, 16, v247
	v_and_b32_e32 v247, 0xffff0000, v247
	v_pk_add_f32 v[194:195], v[194:195], v[244:245]
	v_pk_add_f32 v[220:221], v[220:221], v[246:247]
	v_cvt_pk_bf16_f32 v244, v194, v195
	v_cvt_pk_bf16_f32 v245, v220, v221
	global_store_dwordx2 v[196:197], v[244:245], off offset:80
	v_lshl_add_u64 v[190:191], v[190:191], 0, s[98:99]
	global_load_dword v244, v[190:191], off
	global_load_dword v245, v[190:191], off offset:1024
	global_load_dwordx2 v[246:247], v[192:193], off offset:64
	s_waitcnt vmcnt(24)
	v_lshlrev_b32_e32 v194, 16, v198
	v_and_b32_e32 v195, 0xffff0000, v198
	v_lshlrev_b32_e32 v220, 16, v199
	v_and_b32_e32 v221, 0xffff0000, v199
	v_pk_mul_f32 v[194:195], v[74:75], v[194:195]
	v_pk_mul_f32 v[220:221], v[76:77], v[220:221]
	v_lshlrev_b32_e32 v198, 16, v200
	v_and_b32_e32 v199, 0xffff0000, v200
	v_lshlrev_b32_e32 v200, 16, v201
	v_and_b32_e32 v201, 0xffff0000, v201
	v_pk_add_f32 v[194:195], v[194:195], v[198:199]
	v_pk_add_f32 v[220:221], v[220:221], v[200:201]
	v_cvt_pk_bf16_f32 v198, v194, v195
	v_cvt_pk_bf16_f32 v199, v220, v221
	global_store_dwordx2 v[196:197], v[198:199], off offset:96
	global_load_dword v198, v[190:191], off offset:2048
	global_load_dword v199, v[190:191], off offset:3072
	global_load_dwordx2 v[200:201], v[192:193], off offset:80
	s_waitcnt vmcnt(24)
	v_lshlrev_b32_e32 v194, 16, v202
	v_and_b32_e32 v195, 0xffff0000, v202
	v_lshlrev_b32_e32 v220, 16, v203
	v_and_b32_e32 v221, 0xffff0000, v203
	v_pk_mul_f32 v[194:195], v[78:79], v[194:195]
	v_pk_mul_f32 v[220:221], v[80:81], v[220:221]
	v_lshlrev_b32_e32 v202, 16, v204
	v_and_b32_e32 v203, 0xffff0000, v204
	v_lshlrev_b32_e32 v204, 16, v205
	v_and_b32_e32 v205, 0xffff0000, v205
	v_pk_add_f32 v[194:195], v[194:195], v[202:203]
	v_pk_add_f32 v[220:221], v[220:221], v[204:205]
	v_cvt_pk_bf16_f32 v202, v194, v195
	v_cvt_pk_bf16_f32 v203, v220, v221
	global_store_dwordx2 v[196:197], v[202:203], off offset:112
	v_lshl_add_u64 v[190:191], v[190:191], 0, s[98:99]
	global_load_dword v202, v[190:191], off
	global_load_dword v203, v[190:191], off offset:1024
	global_load_dwordx2 v[204:205], v[192:193], off offset:96
	s_waitcnt vmcnt(24)
	v_lshlrev_b32_e32 v194, 16, v206
	v_and_b32_e32 v195, 0xffff0000, v206
	v_lshlrev_b32_e32 v220, 16, v207
	v_and_b32_e32 v221, 0xffff0000, v207
	v_pk_mul_f32 v[194:195], v[50:51], v[194:195]
	v_pk_mul_f32 v[220:221], v[52:53], v[220:221]
	v_lshlrev_b32_e32 v206, 16, v208
	v_and_b32_e32 v207, 0xffff0000, v208
	v_lshlrev_b32_e32 v208, 16, v209
	v_and_b32_e32 v209, 0xffff0000, v209
	v_pk_add_f32 v[194:195], v[194:195], v[206:207]
	v_pk_add_f32 v[220:221], v[220:221], v[208:209]
	v_cvt_pk_bf16_f32 v206, v194, v195
	v_cvt_pk_bf16_f32 v207, v220, v221
	v_lshl_add_u64 v[196:197], v[196:197], 0, s[90:91]
	global_store_dwordx2 v[196:197], v[206:207], off
	global_load_dword v206, v[190:191], off offset:2048
	global_load_dword v207, v[190:191], off offset:3072
	global_load_dwordx2 v[208:209], v[192:193], off offset:112
	s_waitcnt vmcnt(24)
	v_lshlrev_b32_e32 v194, 16, v216
	v_and_b32_e32 v195, 0xffff0000, v216
	v_lshlrev_b32_e32 v220, 16, v217
	v_and_b32_e32 v221, 0xffff0000, v217
	v_pk_mul_f32 v[194:195], v[54:55], v[194:195]
	v_pk_mul_f32 v[220:221], v[56:57], v[220:221]
	v_lshlrev_b32_e32 v216, 16, v218
	v_and_b32_e32 v217, 0xffff0000, v218
	v_lshlrev_b32_e32 v218, 16, v219
	v_and_b32_e32 v219, 0xffff0000, v219
	v_pk_add_f32 v[194:195], v[194:195], v[216:217]
	v_pk_add_f32 v[220:221], v[220:221], v[218:219]
	v_cvt_pk_bf16_f32 v216, v194, v195
	v_cvt_pk_bf16_f32 v217, v220, v221
	global_store_dwordx2 v[196:197], v[216:217], off offset:16
	v_lshl_add_u64 v[190:191], v[190:191], 0, s[98:99]
	global_load_dword v216, v[190:191], off
	global_load_dword v217, v[190:191], off offset:1024
	v_lshl_add_u64 v[192:193], v[192:193], 0, s[90:91]
	global_load_dwordx2 v[218:219], v[192:193], off
	s_waitcnt vmcnt(24)
	v_lshlrev_b32_e32 v194, 16, v236
	v_and_b32_e32 v195, 0xffff0000, v236
	v_lshlrev_b32_e32 v220, 16, v237
	v_and_b32_e32 v221, 0xffff0000, v237
	v_pk_mul_f32 v[194:195], v[58:59], v[194:195]
	v_pk_mul_f32 v[220:221], v[60:61], v[220:221]
	v_lshlrev_b32_e32 v236, 16, v238
	v_and_b32_e32 v237, 0xffff0000, v238
	v_lshlrev_b32_e32 v238, 16, v239
	v_and_b32_e32 v239, 0xffff0000, v239
	v_pk_add_f32 v[194:195], v[194:195], v[236:237]
	v_pk_add_f32 v[220:221], v[220:221], v[238:239]
	v_cvt_pk_bf16_f32 v236, v194, v195
	v_cvt_pk_bf16_f32 v237, v220, v221
	global_store_dwordx2 v[196:197], v[236:237], off offset:32
	global_load_dword v236, v[190:191], off offset:2048
	global_load_dword v237, v[190:191], off offset:3072
	global_load_dwordx2 v[238:239], v[192:193], off offset:16
	s_waitcnt vmcnt(24)
	v_lshlrev_b32_e32 v194, 16, v240
	v_and_b32_e32 v195, 0xffff0000, v240
	v_lshlrev_b32_e32 v220, 16, v241
	v_and_b32_e32 v221, 0xffff0000, v241
	v_pk_mul_f32 v[194:195], v[62:63], v[194:195]
	v_pk_mul_f32 v[220:221], v[64:65], v[220:221]
	v_lshlrev_b32_e32 v240, 16, v242
	v_and_b32_e32 v241, 0xffff0000, v242
	v_lshlrev_b32_e32 v242, 16, v243
	v_and_b32_e32 v243, 0xffff0000, v243
	v_pk_add_f32 v[194:195], v[194:195], v[240:241]
	v_pk_add_f32 v[220:221], v[220:221], v[242:243]
	v_cvt_pk_bf16_f32 v240, v194, v195
	v_cvt_pk_bf16_f32 v241, v220, v221
	global_store_dwordx2 v[196:197], v[240:241], off offset:48
	v_lshl_add_u64 v[190:191], v[190:191], 0, s[98:99]
	global_load_dword v240, v[190:191], off
	global_load_dword v241, v[190:191], off offset:1024
	global_load_dwordx2 v[242:243], v[192:193], off offset:32
	s_waitcnt vmcnt(24)
	v_lshlrev_b32_e32 v194, 16, v244
	v_and_b32_e32 v195, 0xffff0000, v244
	v_lshlrev_b32_e32 v220, 16, v245
	v_and_b32_e32 v221, 0xffff0000, v245
	v_pk_mul_f32 v[194:195], v[34:35], v[194:195]
	v_pk_mul_f32 v[220:221], v[36:37], v[220:221]
	v_lshlrev_b32_e32 v244, 16, v246
	v_and_b32_e32 v245, 0xffff0000, v246
	v_lshlrev_b32_e32 v246, 16, v247
	v_and_b32_e32 v247, 0xffff0000, v247
	v_pk_add_f32 v[194:195], v[194:195], v[244:245]
	v_pk_add_f32 v[220:221], v[220:221], v[246:247]
	v_cvt_pk_bf16_f32 v244, v194, v195
	v_cvt_pk_bf16_f32 v245, v220, v221
	global_store_dwordx2 v[196:197], v[244:245], off offset:64
	global_load_dword v244, v[190:191], off offset:2048
	global_load_dword v245, v[190:191], off offset:3072
	global_load_dwordx2 v[246:247], v[192:193], off offset:48
	s_waitcnt vmcnt(24)
	v_lshlrev_b32_e32 v194, 16, v198
	v_and_b32_e32 v195, 0xffff0000, v198
	v_lshlrev_b32_e32 v220, 16, v199
	v_and_b32_e32 v221, 0xffff0000, v199
	v_pk_mul_f32 v[194:195], v[38:39], v[194:195]
	v_pk_mul_f32 v[220:221], v[40:41], v[220:221]
	v_lshlrev_b32_e32 v198, 16, v200
	v_and_b32_e32 v199, 0xffff0000, v200
	v_lshlrev_b32_e32 v200, 16, v201
	v_and_b32_e32 v201, 0xffff0000, v201
	v_pk_add_f32 v[194:195], v[194:195], v[198:199]
	v_pk_add_f32 v[220:221], v[220:221], v[200:201]
	v_cvt_pk_bf16_f32 v198, v194, v195
	v_cvt_pk_bf16_f32 v199, v220, v221
	global_store_dwordx2 v[196:197], v[198:199], off offset:80
	v_lshl_add_u64 v[190:191], v[190:191], 0, s[98:99]
	global_load_dword v198, v[190:191], off
	global_load_dword v199, v[190:191], off offset:1024
	global_load_dwordx2 v[200:201], v[192:193], off offset:64
	s_waitcnt vmcnt(24)
	v_lshlrev_b32_e32 v194, 16, v202
	v_and_b32_e32 v195, 0xffff0000, v202
	v_lshlrev_b32_e32 v220, 16, v203
	v_and_b32_e32 v221, 0xffff0000, v203
	v_pk_mul_f32 v[194:195], v[42:43], v[194:195]
	v_pk_mul_f32 v[220:221], v[44:45], v[220:221]
	v_lshlrev_b32_e32 v202, 16, v204
	v_and_b32_e32 v203, 0xffff0000, v204
	v_lshlrev_b32_e32 v204, 16, v205
	v_and_b32_e32 v205, 0xffff0000, v205
	v_pk_add_f32 v[194:195], v[194:195], v[202:203]
	v_pk_add_f32 v[220:221], v[220:221], v[204:205]
	v_cvt_pk_bf16_f32 v202, v194, v195
	v_cvt_pk_bf16_f32 v203, v220, v221
	global_store_dwordx2 v[196:197], v[202:203], off offset:96
	global_load_dword v202, v[190:191], off offset:2048
	global_load_dword v203, v[190:191], off offset:3072
	global_load_dwordx2 v[204:205], v[192:193], off offset:80
	s_waitcnt vmcnt(24)
	v_lshlrev_b32_e32 v194, 16, v206
	v_and_b32_e32 v195, 0xffff0000, v206
	v_lshlrev_b32_e32 v220, 16, v207
	v_and_b32_e32 v221, 0xffff0000, v207
	v_pk_mul_f32 v[194:195], v[46:47], v[194:195]
	v_pk_mul_f32 v[220:221], v[48:49], v[220:221]
	v_lshlrev_b32_e32 v206, 16, v208
	v_and_b32_e32 v207, 0xffff0000, v208
	v_lshlrev_b32_e32 v208, 16, v209
	v_and_b32_e32 v209, 0xffff0000, v209
	v_pk_add_f32 v[194:195], v[194:195], v[206:207]
	v_pk_add_f32 v[220:221], v[220:221], v[208:209]
	v_cvt_pk_bf16_f32 v206, v194, v195
	v_cvt_pk_bf16_f32 v207, v220, v221
	global_store_dwordx2 v[196:197], v[206:207], off offset:112
	v_lshl_add_u64 v[190:191], v[190:191], 0, s[98:99]
	global_load_dword v206, v[190:191], off
	global_load_dword v207, v[190:191], off offset:1024
	global_load_dwordx2 v[208:209], v[192:193], off offset:96
	s_waitcnt vmcnt(24)
	v_lshlrev_b32_e32 v194, 16, v216
	v_and_b32_e32 v195, 0xffff0000, v216
	v_lshlrev_b32_e32 v220, 16, v217
	v_and_b32_e32 v221, 0xffff0000, v217
	v_pk_mul_f32 v[194:195], v[18:19], v[194:195]
	v_pk_mul_f32 v[220:221], v[20:21], v[220:221]
	v_lshlrev_b32_e32 v216, 16, v218
	v_and_b32_e32 v217, 0xffff0000, v218
	v_lshlrev_b32_e32 v218, 16, v219
	v_and_b32_e32 v219, 0xffff0000, v219
	v_pk_add_f32 v[194:195], v[194:195], v[216:217]
	v_pk_add_f32 v[220:221], v[220:221], v[218:219]
	v_cvt_pk_bf16_f32 v216, v194, v195
	v_cvt_pk_bf16_f32 v217, v220, v221
	v_lshl_add_u64 v[196:197], v[196:197], 0, s[90:91]
	global_store_dwordx2 v[196:197], v[216:217], off
	global_load_dword v216, v[190:191], off offset:2048
	global_load_dword v217, v[190:191], off offset:3072
	global_load_dwordx2 v[218:219], v[192:193], off offset:112
	s_waitcnt vmcnt(24)
	v_lshlrev_b32_e32 v194, 16, v236
	v_and_b32_e32 v195, 0xffff0000, v236
	v_lshlrev_b32_e32 v220, 16, v237
	v_and_b32_e32 v221, 0xffff0000, v237
	v_pk_mul_f32 v[194:195], v[22:23], v[194:195]
	v_pk_mul_f32 v[220:221], v[24:25], v[220:221]
	v_lshlrev_b32_e32 v236, 16, v238
	v_and_b32_e32 v237, 0xffff0000, v238
	v_lshlrev_b32_e32 v238, 16, v239
	v_and_b32_e32 v239, 0xffff0000, v239
	v_pk_add_f32 v[194:195], v[194:195], v[236:237]
	v_pk_add_f32 v[220:221], v[220:221], v[238:239]
	v_cvt_pk_bf16_f32 v236, v194, v195
	v_cvt_pk_bf16_f32 v237, v220, v221
	global_store_dwordx2 v[196:197], v[236:237], off offset:16
	s_waitcnt vmcnt(21)
	v_lshlrev_b32_e32 v194, 16, v240
	v_and_b32_e32 v195, 0xffff0000, v240
	v_lshlrev_b32_e32 v220, 16, v241
	v_and_b32_e32 v221, 0xffff0000, v241
	v_pk_mul_f32 v[194:195], v[26:27], v[194:195]
	v_pk_mul_f32 v[220:221], v[28:29], v[220:221]
	v_lshlrev_b32_e32 v240, 16, v242
	v_and_b32_e32 v241, 0xffff0000, v242
	v_lshlrev_b32_e32 v242, 16, v243
	v_and_b32_e32 v243, 0xffff0000, v243
	v_pk_add_f32 v[194:195], v[194:195], v[240:241]
	v_pk_add_f32 v[220:221], v[220:221], v[242:243]
	v_cvt_pk_bf16_f32 v240, v194, v195
	v_cvt_pk_bf16_f32 v241, v220, v221
	global_store_dwordx2 v[196:197], v[240:241], off offset:32
	s_waitcnt vmcnt(18)
	v_lshlrev_b32_e32 v194, 16, v244
	v_and_b32_e32 v195, 0xffff0000, v244
	v_lshlrev_b32_e32 v220, 16, v245
	v_and_b32_e32 v221, 0xffff0000, v245
	v_pk_mul_f32 v[194:195], v[30:31], v[194:195]
	v_pk_mul_f32 v[220:221], v[32:33], v[220:221]
	v_lshlrev_b32_e32 v244, 16, v246
	v_and_b32_e32 v245, 0xffff0000, v246
	v_lshlrev_b32_e32 v246, 16, v247
	v_and_b32_e32 v247, 0xffff0000, v247
	v_pk_add_f32 v[194:195], v[194:195], v[244:245]
	v_pk_add_f32 v[220:221], v[220:221], v[246:247]
	v_cvt_pk_bf16_f32 v244, v194, v195
	v_cvt_pk_bf16_f32 v245, v220, v221
	global_store_dwordx2 v[196:197], v[244:245], off offset:48
	s_waitcnt vmcnt(15)
	v_lshlrev_b32_e32 v194, 16, v198
	v_and_b32_e32 v195, 0xffff0000, v198
	v_lshlrev_b32_e32 v220, 16, v199
	v_and_b32_e32 v221, 0xffff0000, v199
	v_pk_mul_f32 v[194:195], v[2:3], v[194:195]
	v_pk_mul_f32 v[220:221], v[4:5], v[220:221]
	v_lshlrev_b32_e32 v198, 16, v200
	v_and_b32_e32 v199, 0xffff0000, v200
	v_lshlrev_b32_e32 v200, 16, v201
	v_and_b32_e32 v201, 0xffff0000, v201
	v_pk_add_f32 v[194:195], v[194:195], v[198:199]
	v_pk_add_f32 v[220:221], v[220:221], v[200:201]
	v_cvt_pk_bf16_f32 v198, v194, v195
	v_cvt_pk_bf16_f32 v199, v220, v221
	global_store_dwordx2 v[196:197], v[198:199], off offset:64
	s_waitcnt vmcnt(12)
	v_lshlrev_b32_e32 v194, 16, v202
	v_and_b32_e32 v195, 0xffff0000, v202
	v_lshlrev_b32_e32 v220, 16, v203
	v_and_b32_e32 v221, 0xffff0000, v203
	v_pk_mul_f32 v[194:195], v[6:7], v[194:195]
	v_pk_mul_f32 v[220:221], v[8:9], v[220:221]
	v_lshlrev_b32_e32 v202, 16, v204
	v_and_b32_e32 v203, 0xffff0000, v204
	v_lshlrev_b32_e32 v204, 16, v205
	v_and_b32_e32 v205, 0xffff0000, v205
	v_pk_add_f32 v[194:195], v[194:195], v[202:203]
	v_pk_add_f32 v[220:221], v[220:221], v[204:205]
	v_cvt_pk_bf16_f32 v202, v194, v195
	v_cvt_pk_bf16_f32 v203, v220, v221
	global_store_dwordx2 v[196:197], v[202:203], off offset:80
	s_waitcnt vmcnt(9)
	v_lshlrev_b32_e32 v194, 16, v206
	v_and_b32_e32 v195, 0xffff0000, v206
	v_lshlrev_b32_e32 v220, 16, v207
	v_and_b32_e32 v221, 0xffff0000, v207
	v_pk_mul_f32 v[194:195], v[10:11], v[194:195]
	v_pk_mul_f32 v[220:221], v[12:13], v[220:221]
	v_lshlrev_b32_e32 v206, 16, v208
	v_and_b32_e32 v207, 0xffff0000, v208
	v_lshlrev_b32_e32 v208, 16, v209
	v_and_b32_e32 v209, 0xffff0000, v209
	v_pk_add_f32 v[194:195], v[194:195], v[206:207]
	v_pk_add_f32 v[220:221], v[220:221], v[208:209]
	v_cvt_pk_bf16_f32 v206, v194, v195
	v_cvt_pk_bf16_f32 v207, v220, v221
	global_store_dwordx2 v[196:197], v[206:207], off offset:96
	s_waitcnt vmcnt(6)
	v_lshlrev_b32_e32 v194, 16, v216
	v_and_b32_e32 v195, 0xffff0000, v216
	v_lshlrev_b32_e32 v220, 16, v217
	v_and_b32_e32 v221, 0xffff0000, v217
	v_pk_mul_f32 v[194:195], v[14:15], v[194:195]
	v_pk_mul_f32 v[220:221], v[16:17], v[220:221]
	v_lshlrev_b32_e32 v216, 16, v218
	v_and_b32_e32 v217, 0xffff0000, v218
	v_lshlrev_b32_e32 v218, 16, v219
	v_and_b32_e32 v219, 0xffff0000, v219
	v_pk_add_f32 v[194:195], v[194:195], v[216:217]
	v_pk_add_f32 v[220:221], v[220:221], v[218:219]
	v_cvt_pk_bf16_f32 v216, v194, v195
	v_cvt_pk_bf16_f32 v217, v220, v221
	global_store_dwordx2 v[196:197], v[216:217], off offset:112
	s_branch .Lme_done
.Lme_noold:
	s_waitcnt vmcnt(12)
	v_lshlrev_b32_e32 v194, 16, v198
	v_and_b32_e32 v195, 0xffff0000, v198
	v_lshlrev_b32_e32 v220, 16, v199
	v_and_b32_e32 v221, 0xffff0000, v199
	v_pk_mul_f32 v[194:195], v[114:115], v[194:195]
	v_pk_mul_f32 v[220:221], v[116:117], v[220:221]
	v_cvt_pk_bf16_f32 v198, v194, v195
	v_cvt_pk_bf16_f32 v199, v220, v221
	global_store_dwordx2 v[196:197], v[198:199], off
	global_load_dword v198, v[190:191], off offset:2048
	global_load_dword v199, v[190:191], off offset:3072
	s_waitcnt vmcnt(13)
	v_lshlrev_b32_e32 v194, 16, v202
	v_and_b32_e32 v195, 0xffff0000, v202
	v_lshlrev_b32_e32 v220, 16, v203
	v_and_b32_e32 v221, 0xffff0000, v203
	v_pk_mul_f32 v[194:195], v[118:119], v[194:195]
	v_pk_mul_f32 v[220:221], v[120:121], v[220:221]
	v_cvt_pk_bf16_f32 v202, v194, v195
	v_cvt_pk_bf16_f32 v203, v220, v221
	global_store_dwordx2 v[196:197], v[202:203], off offset:16
	v_lshl_add_u64 v[190:191], v[190:191], 0, s[98:99]
	global_load_dword v202, v[190:191], off
	global_load_dword v203, v[190:191], off offset:1024
	s_waitcnt vmcnt(14)
	v_lshlrev_b32_e32 v194, 16, v206
	v_and_b32_e32 v195, 0xffff0000, v206
	v_lshlrev_b32_e32 v220, 16, v207
	v_and_b32_e32 v221, 0xffff0000, v207
	v_pk_mul_f32 v[194:195], v[122:123], v[194:195]
	v_pk_mul_f32 v[220:221], v[124:125], v[220:221]
	v_cvt_pk_bf16_f32 v206, v194, v195
	v_cvt_pk_bf16_f32 v207, v220, v221
	global_store_dwordx2 v[196:197], v[206:207], off offset:32
	global_load_dword v206, v[190:191], off offset:2048
	global_load_dword v207, v[190:191], off offset:3072
	s_waitcnt vmcnt(15)
	v_lshlrev_b32_e32 v194, 16, v216
	v_and_b32_e32 v195, 0xffff0000, v216
	v_lshlrev_b32_e32 v220, 16, v217
	v_and_b32_e32 v221, 0xffff0000, v217
	v_pk_mul_f32 v[194:195], v[126:127], v[194:195]
	v_pk_mul_f32 v[220:221], v[128:129], v[220:221]
	v_cvt_pk_bf16_f32 v216, v194, v195
	v_cvt_pk_bf16_f32 v217, v220, v221
	global_store_dwordx2 v[196:197], v[216:217], off offset:48
	v_lshl_add_u64 v[190:191], v[190:191], 0, s[98:99]
	global_load_dword v216, v[190:191], off
	global_load_dword v217, v[190:191], off offset:1024
	s_waitcnt vmcnt(16)
	v_lshlrev_b32_e32 v194, 16, v236
	v_and_b32_e32 v195, 0xffff0000, v236
	v_lshlrev_b32_e32 v220, 16, v237
	v_and_b32_e32 v221, 0xffff0000, v237
	v_pk_mul_f32 v[194:195], v[98:99], v[194:195]
	v_pk_mul_f32 v[220:221], v[100:101], v[220:221]
	v_cvt_pk_bf16_f32 v236, v194, v195
	v_cvt_pk_bf16_f32 v237, v220, v221
	global_store_dwordx2 v[196:197], v[236:237], off offset:64
	global_load_dword v236, v[190:191], off offset:2048
	global_load_dword v237, v[190:191], off offset:3072
	s_waitcnt vmcnt(17)
	v_lshlrev_b32_e32 v194, 16, v240
	v_and_b32_e32 v195, 0xffff0000, v240
	v_lshlrev_b32_e32 v220, 16, v241
	v_and_b32_e32 v221, 0xffff0000, v241
	v_pk_mul_f32 v[194:195], v[102:103], v[194:195]
	v_pk_mul_f32 v[220:221], v[104:105], v[220:221]
	v_cvt_pk_bf16_f32 v240, v194, v195
	v_cvt_pk_bf16_f32 v241, v220, v221
	global_store_dwordx2 v[196:197], v[240:241], off offset:80
	v_lshl_add_u64 v[190:191], v[190:191], 0, s[98:99]
	global_load_dword v240, v[190:191], off
	global_load_dword v241, v[190:191], off offset:1024
	s_waitcnt vmcnt(18)
	v_lshlrev_b32_e32 v194, 16, v244
	v_and_b32_e32 v195, 0xffff0000, v244
	v_lshlrev_b32_e32 v220, 16, v245
	v_and_b32_e32 v221, 0xffff0000, v245
	v_pk_mul_f32 v[194:195], v[106:107], v[194:195]
	v_pk_mul_f32 v[220:221], v[108:109], v[220:221]
	v_cvt_pk_bf16_f32 v244, v194, v195
	v_cvt_pk_bf16_f32 v245, v220, v221
	global_store_dwordx2 v[196:197], v[244:245], off offset:96
	global_load_dword v244, v[190:191], off offset:2048
	global_load_dword v245, v[190:191], off offset:3072
	s_waitcnt vmcnt(18)
	v_lshlrev_b32_e32 v194, 16, v198
	v_and_b32_e32 v195, 0xffff0000, v198
	v_lshlrev_b32_e32 v220, 16, v199
	v_and_b32_e32 v221, 0xffff0000, v199
	v_pk_mul_f32 v[194:195], v[110:111], v[194:195]
	v_pk_mul_f32 v[220:221], v[112:113], v[220:221]
	v_cvt_pk_bf16_f32 v198, v194, v195
	v_cvt_pk_bf16_f32 v199, v220, v221
	global_store_dwordx2 v[196:197], v[198:199], off offset:112
	v_lshl_add_u64 v[190:191], v[190:191], 0, s[98:99]
	global_load_dword v198, v[190:191], off
	global_load_dword v199, v[190:191], off offset:1024
	s_waitcnt vmcnt(18)
	v_lshlrev_b32_e32 v194, 16, v202
	v_and_b32_e32 v195, 0xffff0000, v202
	v_lshlrev_b32_e32 v220, 16, v203
	v_and_b32_e32 v221, 0xffff0000, v203
	v_pk_mul_f32 v[194:195], v[82:83], v[194:195]
	v_pk_mul_f32 v[220:221], v[84:85], v[220:221]
	v_cvt_pk_bf16_f32 v202, v194, v195
	v_cvt_pk_bf16_f32 v203, v220, v221
	v_lshl_add_u64 v[196:197], v[196:197], 0, s[90:91]
	global_store_dwordx2 v[196:197], v[202:203], off
	global_load_dword v202, v[190:191], off offset:2048
	global_load_dword v203, v[190:191], off offset:3072
	s_waitcnt vmcnt(18)
	v_lshlrev_b32_e32 v194, 16, v206
	v_and_b32_e32 v195, 0xffff0000, v206
	v_lshlrev_b32_e32 v220, 16, v207
	v_and_b32_e32 v221, 0xffff0000, v207
	v_pk_mul_f32 v[194:195], v[86:87], v[194:195]
	v_pk_mul_f32 v[220:221], v[88:89], v[220:221]
	v_cvt_pk_bf16_f32 v206, v194, v195
	v_cvt_pk_bf16_f32 v207, v220, v221
	global_store_dwordx2 v[196:197], v[206:207], off offset:16
	v_lshl_add_u64 v[190:191], v[190:191], 0, s[98:99]
	global_load_dword v206, v[190:191], off
	global_load_dword v207, v[190:191], off offset:1024
	s_waitcnt vmcnt(18)
	v_lshlrev_b32_e32 v194, 16, v216
	v_and_b32_e32 v195, 0xffff0000, v216
	v_lshlrev_b32_e32 v220, 16, v217
	v_and_b32_e32 v221, 0xffff0000, v217
	v_pk_mul_f32 v[194:195], v[90:91], v[194:195]
	v_pk_mul_f32 v[220:221], v[92:93], v[220:221]
	v_cvt_pk_bf16_f32 v216, v194, v195
	v_cvt_pk_bf16_f32 v217, v220, v221
	global_store_dwordx2 v[196:197], v[216:217], off offset:32
	global_load_dword v216, v[190:191], off offset:2048
	global_load_dword v217, v[190:191], off offset:3072
	s_waitcnt vmcnt(18)
	v_lshlrev_b32_e32 v194, 16, v236
	v_and_b32_e32 v195, 0xffff0000, v236
	v_lshlrev_b32_e32 v220, 16, v237
	v_and_b32_e32 v221, 0xffff0000, v237
	v_pk_mul_f32 v[194:195], v[94:95], v[194:195]
	v_pk_mul_f32 v[220:221], v[96:97], v[220:221]
	v_cvt_pk_bf16_f32 v236, v194, v195
	v_cvt_pk_bf16_f32 v237, v220, v221
	global_store_dwordx2 v[196:197], v[236:237], off offset:48
	v_lshl_add_u64 v[190:191], v[190:191], 0, s[98:99]
	global_load_dword v236, v[190:191], off
	global_load_dword v237, v[190:191], off offset:1024
	s_waitcnt vmcnt(18)
	v_lshlrev_b32_e32 v194, 16, v240
	v_and_b32_e32 v195, 0xffff0000, v240
	v_lshlrev_b32_e32 v220, 16, v241
	v_and_b32_e32 v221, 0xffff0000, v241
	v_pk_mul_f32 v[194:195], v[66:67], v[194:195]
	v_pk_mul_f32 v[220:221], v[68:69], v[220:221]
	v_cvt_pk_bf16_f32 v240, v194, v195
	v_cvt_pk_bf16_f32 v241, v220, v221
	global_store_dwordx2 v[196:197], v[240:241], off offset:64
	global_load_dword v240, v[190:191], off offset:2048
	global_load_dword v241, v[190:191], off offset:3072
	s_waitcnt vmcnt(18)
	v_lshlrev_b32_e32 v194, 16, v244
	v_and_b32_e32 v195, 0xffff0000, v244
	v_lshlrev_b32_e32 v220, 16, v245
	v_and_b32_e32 v221, 0xffff0000, v245
	v_pk_mul_f32 v[194:195], v[70:71], v[194:195]
	v_pk_mul_f32 v[220:221], v[72:73], v[220:221]
	v_cvt_pk_bf16_f32 v244, v194, v195
	v_cvt_pk_bf16_f32 v245, v220, v221
	global_store_dwordx2 v[196:197], v[244:245], off offset:80
	v_lshl_add_u64 v[190:191], v[190:191], 0, s[98:99]
	global_load_dword v244, v[190:191], off
	global_load_dword v245, v[190:191], off offset:1024
	s_waitcnt vmcnt(18)
	v_lshlrev_b32_e32 v194, 16, v198
	v_and_b32_e32 v195, 0xffff0000, v198
	v_lshlrev_b32_e32 v220, 16, v199
	v_and_b32_e32 v221, 0xffff0000, v199
	v_pk_mul_f32 v[194:195], v[74:75], v[194:195]
	v_pk_mul_f32 v[220:221], v[76:77], v[220:221]
	v_cvt_pk_bf16_f32 v198, v194, v195
	v_cvt_pk_bf16_f32 v199, v220, v221
	global_store_dwordx2 v[196:197], v[198:199], off offset:96
	global_load_dword v198, v[190:191], off offset:2048
	global_load_dword v199, v[190:191], off offset:3072
	s_waitcnt vmcnt(18)
	v_lshlrev_b32_e32 v194, 16, v202
	v_and_b32_e32 v195, 0xffff0000, v202
	v_lshlrev_b32_e32 v220, 16, v203
	v_and_b32_e32 v221, 0xffff0000, v203
	v_pk_mul_f32 v[194:195], v[78:79], v[194:195]
	v_pk_mul_f32 v[220:221], v[80:81], v[220:221]
	v_cvt_pk_bf16_f32 v202, v194, v195
	v_cvt_pk_bf16_f32 v203, v220, v221
	global_store_dwordx2 v[196:197], v[202:203], off offset:112
	v_lshl_add_u64 v[190:191], v[190:191], 0, s[98:99]
	global_load_dword v202, v[190:191], off
	global_load_dword v203, v[190:191], off offset:1024
	s_waitcnt vmcnt(18)
	v_lshlrev_b32_e32 v194, 16, v206
	v_and_b32_e32 v195, 0xffff0000, v206
	v_lshlrev_b32_e32 v220, 16, v207
	v_and_b32_e32 v221, 0xffff0000, v207
	v_pk_mul_f32 v[194:195], v[50:51], v[194:195]
	v_pk_mul_f32 v[220:221], v[52:53], v[220:221]
	v_cvt_pk_bf16_f32 v206, v194, v195
	v_cvt_pk_bf16_f32 v207, v220, v221
	v_lshl_add_u64 v[196:197], v[196:197], 0, s[90:91]
	global_store_dwordx2 v[196:197], v[206:207], off
	global_load_dword v206, v[190:191], off offset:2048
	global_load_dword v207, v[190:191], off offset:3072
	s_waitcnt vmcnt(18)
	v_lshlrev_b32_e32 v194, 16, v216
	v_and_b32_e32 v195, 0xffff0000, v216
	v_lshlrev_b32_e32 v220, 16, v217
	v_and_b32_e32 v221, 0xffff0000, v217
	v_pk_mul_f32 v[194:195], v[54:55], v[194:195]
	v_pk_mul_f32 v[220:221], v[56:57], v[220:221]
	v_cvt_pk_bf16_f32 v216, v194, v195
	v_cvt_pk_bf16_f32 v217, v220, v221
	global_store_dwordx2 v[196:197], v[216:217], off offset:16
	v_lshl_add_u64 v[190:191], v[190:191], 0, s[98:99]
	global_load_dword v216, v[190:191], off
	global_load_dword v217, v[190:191], off offset:1024
	s_waitcnt vmcnt(18)
	v_lshlrev_b32_e32 v194, 16, v236
	v_and_b32_e32 v195, 0xffff0000, v236
	v_lshlrev_b32_e32 v220, 16, v237
	v_and_b32_e32 v221, 0xffff0000, v237
	v_pk_mul_f32 v[194:195], v[58:59], v[194:195]
	v_pk_mul_f32 v[220:221], v[60:61], v[220:221]
	v_cvt_pk_bf16_f32 v236, v194, v195
	v_cvt_pk_bf16_f32 v237, v220, v221
	global_store_dwordx2 v[196:197], v[236:237], off offset:32
	global_load_dword v236, v[190:191], off offset:2048
	global_load_dword v237, v[190:191], off offset:3072
	s_waitcnt vmcnt(18)
	v_lshlrev_b32_e32 v194, 16, v240
	v_and_b32_e32 v195, 0xffff0000, v240
	v_lshlrev_b32_e32 v220, 16, v241
	v_and_b32_e32 v221, 0xffff0000, v241
	v_pk_mul_f32 v[194:195], v[62:63], v[194:195]
	v_pk_mul_f32 v[220:221], v[64:65], v[220:221]
	v_cvt_pk_bf16_f32 v240, v194, v195
	v_cvt_pk_bf16_f32 v241, v220, v221
	global_store_dwordx2 v[196:197], v[240:241], off offset:48
	v_lshl_add_u64 v[190:191], v[190:191], 0, s[98:99]
	global_load_dword v240, v[190:191], off
	global_load_dword v241, v[190:191], off offset:1024
	s_waitcnt vmcnt(18)
	v_lshlrev_b32_e32 v194, 16, v244
	v_and_b32_e32 v195, 0xffff0000, v244
	v_lshlrev_b32_e32 v220, 16, v245
	v_and_b32_e32 v221, 0xffff0000, v245
	v_pk_mul_f32 v[194:195], v[34:35], v[194:195]
	v_pk_mul_f32 v[220:221], v[36:37], v[220:221]
	v_cvt_pk_bf16_f32 v244, v194, v195
	v_cvt_pk_bf16_f32 v245, v220, v221
	global_store_dwordx2 v[196:197], v[244:245], off offset:64
	global_load_dword v244, v[190:191], off offset:2048
	global_load_dword v245, v[190:191], off offset:3072
	s_waitcnt vmcnt(18)
	v_lshlrev_b32_e32 v194, 16, v198
	v_and_b32_e32 v195, 0xffff0000, v198
	v_lshlrev_b32_e32 v220, 16, v199
	v_and_b32_e32 v221, 0xffff0000, v199
	v_pk_mul_f32 v[194:195], v[38:39], v[194:195]
	v_pk_mul_f32 v[220:221], v[40:41], v[220:221]
	v_cvt_pk_bf16_f32 v198, v194, v195
	v_cvt_pk_bf16_f32 v199, v220, v221
	global_store_dwordx2 v[196:197], v[198:199], off offset:80
	v_lshl_add_u64 v[190:191], v[190:191], 0, s[98:99]
	global_load_dword v198, v[190:191], off
	global_load_dword v199, v[190:191], off offset:1024
	s_waitcnt vmcnt(18)
	v_lshlrev_b32_e32 v194, 16, v202
	v_and_b32_e32 v195, 0xffff0000, v202
	v_lshlrev_b32_e32 v220, 16, v203
	v_and_b32_e32 v221, 0xffff0000, v203
	v_pk_mul_f32 v[194:195], v[42:43], v[194:195]
	v_pk_mul_f32 v[220:221], v[44:45], v[220:221]
	v_cvt_pk_bf16_f32 v202, v194, v195
	v_cvt_pk_bf16_f32 v203, v220, v221
	global_store_dwordx2 v[196:197], v[202:203], off offset:96
	global_load_dword v202, v[190:191], off offset:2048
	global_load_dword v203, v[190:191], off offset:3072
	s_waitcnt vmcnt(18)
	v_lshlrev_b32_e32 v194, 16, v206
	v_and_b32_e32 v195, 0xffff0000, v206
	v_lshlrev_b32_e32 v220, 16, v207
	v_and_b32_e32 v221, 0xffff0000, v207
	v_pk_mul_f32 v[194:195], v[46:47], v[194:195]
	v_pk_mul_f32 v[220:221], v[48:49], v[220:221]
	v_cvt_pk_bf16_f32 v206, v194, v195
	v_cvt_pk_bf16_f32 v207, v220, v221
	global_store_dwordx2 v[196:197], v[206:207], off offset:112
	v_lshl_add_u64 v[190:191], v[190:191], 0, s[98:99]
	global_load_dword v206, v[190:191], off
	global_load_dword v207, v[190:191], off offset:1024
	s_waitcnt vmcnt(18)
	v_lshlrev_b32_e32 v194, 16, v216
	v_and_b32_e32 v195, 0xffff0000, v216
	v_lshlrev_b32_e32 v220, 16, v217
	v_and_b32_e32 v221, 0xffff0000, v217
	v_pk_mul_f32 v[194:195], v[18:19], v[194:195]
	v_pk_mul_f32 v[220:221], v[20:21], v[220:221]
	v_cvt_pk_bf16_f32 v216, v194, v195
	v_cvt_pk_bf16_f32 v217, v220, v221
	v_lshl_add_u64 v[196:197], v[196:197], 0, s[90:91]
	global_store_dwordx2 v[196:197], v[216:217], off
	global_load_dword v216, v[190:191], off offset:2048
	global_load_dword v217, v[190:191], off offset:3072
	s_waitcnt vmcnt(18)
	v_lshlrev_b32_e32 v194, 16, v236
	v_and_b32_e32 v195, 0xffff0000, v236
	v_lshlrev_b32_e32 v220, 16, v237
	v_and_b32_e32 v221, 0xffff0000, v237
	v_pk_mul_f32 v[194:195], v[22:23], v[194:195]
	v_pk_mul_f32 v[220:221], v[24:25], v[220:221]
	v_cvt_pk_bf16_f32 v236, v194, v195
	v_cvt_pk_bf16_f32 v237, v220, v221
	global_store_dwordx2 v[196:197], v[236:237], off offset:16
	s_waitcnt vmcnt(16)
	v_lshlrev_b32_e32 v194, 16, v240
	v_and_b32_e32 v195, 0xffff0000, v240
	v_lshlrev_b32_e32 v220, 16, v241
	v_and_b32_e32 v221, 0xffff0000, v241
	v_pk_mul_f32 v[194:195], v[26:27], v[194:195]
	v_pk_mul_f32 v[220:221], v[28:29], v[220:221]
	v_cvt_pk_bf16_f32 v240, v194, v195
	v_cvt_pk_bf16_f32 v241, v220, v221
	global_store_dwordx2 v[196:197], v[240:241], off offset:32
	s_waitcnt vmcnt(14)
	v_lshlrev_b32_e32 v194, 16, v244
	v_and_b32_e32 v195, 0xffff0000, v244
	v_lshlrev_b32_e32 v220, 16, v245
	v_and_b32_e32 v221, 0xffff0000, v245
	v_pk_mul_f32 v[194:195], v[30:31], v[194:195]
	v_pk_mul_f32 v[220:221], v[32:33], v[220:221]
	v_cvt_pk_bf16_f32 v244, v194, v195
	v_cvt_pk_bf16_f32 v245, v220, v221
	global_store_dwordx2 v[196:197], v[244:245], off offset:48
	s_waitcnt vmcnt(12)
	v_lshlrev_b32_e32 v194, 16, v198
	v_and_b32_e32 v195, 0xffff0000, v198
	v_lshlrev_b32_e32 v220, 16, v199
	v_and_b32_e32 v221, 0xffff0000, v199
	v_pk_mul_f32 v[194:195], v[2:3], v[194:195]
	v_pk_mul_f32 v[220:221], v[4:5], v[220:221]
	v_cvt_pk_bf16_f32 v198, v194, v195
	v_cvt_pk_bf16_f32 v199, v220, v221
	global_store_dwordx2 v[196:197], v[198:199], off offset:64
	s_waitcnt vmcnt(10)
	v_lshlrev_b32_e32 v194, 16, v202
	v_and_b32_e32 v195, 0xffff0000, v202
	v_lshlrev_b32_e32 v220, 16, v203
	v_and_b32_e32 v221, 0xffff0000, v203
	v_pk_mul_f32 v[194:195], v[6:7], v[194:195]
	v_pk_mul_f32 v[220:221], v[8:9], v[220:221]
	v_cvt_pk_bf16_f32 v202, v194, v195
	v_cvt_pk_bf16_f32 v203, v220, v221
	global_store_dwordx2 v[196:197], v[202:203], off offset:80
	s_waitcnt vmcnt(8)
	v_lshlrev_b32_e32 v194, 16, v206
	v_and_b32_e32 v195, 0xffff0000, v206
	v_lshlrev_b32_e32 v220, 16, v207
	v_and_b32_e32 v221, 0xffff0000, v207
	v_pk_mul_f32 v[194:195], v[10:11], v[194:195]
	v_pk_mul_f32 v[220:221], v[12:13], v[220:221]
	v_cvt_pk_bf16_f32 v206, v194, v195
	v_cvt_pk_bf16_f32 v207, v220, v221
	global_store_dwordx2 v[196:197], v[206:207], off offset:96
	s_waitcnt vmcnt(6)
	v_lshlrev_b32_e32 v194, 16, v216
	v_and_b32_e32 v195, 0xffff0000, v216
	v_lshlrev_b32_e32 v220, 16, v217
	v_and_b32_e32 v221, 0xffff0000, v217
	v_pk_mul_f32 v[194:195], v[14:15], v[194:195]
	v_pk_mul_f32 v[220:221], v[16:17], v[220:221]
	v_cvt_pk_bf16_f32 v216, v194, v195
	v_cvt_pk_bf16_f32 v217, v220, v221
	global_store_dwordx2 v[196:197], v[216:217], off offset:112
.Lme_done:
	s_mov_b64 s[4:5], 0
.LBB0_159:
	s_mov_b32 s9, 16
	s_and_b64 vcc, exec, s[4:5]
	s_cbranch_vccz .LBB0_77
	v_mul_f32_e32 v0, 0xbfb8aa3b, v114
	v_mul_f32_e32 v114, 0xbfb8aa3b, v115
	v_exp_f32_e32 v0, v0
	v_exp_f32_e32 v114, v114
	v_mul_f32_e32 v115, 0xbfb8aa3b, v116
	v_mul_f32_e32 v116, 0xbfb8aa3b, v117
	v_exp_f32_e32 v115, v115
	v_exp_f32_e32 v116, v116
	v_add_f32_e32 v0, 1.0, v0
	v_add_f32_e32 v114, 1.0, v114
	v_rcp_f32_e32 v0, v0
	v_rcp_f32_e32 v114, v114
	v_add_f32_e32 v115, 1.0, v115
	v_add_f32_e32 v116, 1.0, v116
	v_rcp_f32_e32 v115, v115
	v_rcp_f32_e32 v116, v116
	v_cvt_pk_bf16_f32 v0, v0, v114
	global_store_dword v[190:191], v0, off
	v_mul_f32_e32 v114, 0xbfb8aa3b, v118
	v_cvt_pk_bf16_f32 v0, v115, v116
	v_mul_f32_e32 v115, 0xbfb8aa3b, v119
	v_exp_f32_e32 v114, v114
	v_exp_f32_e32 v115, v115
	global_store_dword v[190:191], v0, off offset:1024
	v_mul_f32_e32 v116, 0xbfb8aa3b, v121
	v_add_f32_e32 v0, 1.0, v114
	v_add_f32_e32 v114, 1.0, v115
	v_mul_f32_e32 v115, 0xbfb8aa3b, v120
	v_rcp_f32_e32 v0, v0
	v_rcp_f32_e32 v114, v114
	v_exp_f32_e32 v115, v115
	v_exp_f32_e32 v116, v116
	v_mul_f32_e32 v117, 0xbfb8aa3b, v123
	v_cvt_pk_bf16_f32 v0, v0, v114
	v_add_f32_e32 v114, 1.0, v115
	v_add_f32_e32 v115, 1.0, v116
	v_mul_f32_e32 v116, 0xbfb8aa3b, v122
	v_exp_f32_e32 v116, v116
	v_exp_f32_e32 v117, v117
	v_rcp_f32_e32 v114, v114
	v_rcp_f32_e32 v115, v115
	v_add_f32_e32 v116, 1.0, v116
	v_add_f32_e32 v117, 1.0, v117
	v_rcp_f32_e32 v116, v116
	v_rcp_f32_e32 v117, v117
	global_store_dword v[190:191], v0, off offset:2048
	v_cvt_pk_bf16_f32 v0, v114, v115
	global_store_dword v[190:191], v0, off offset:3072
	v_cvt_pk_bf16_f32 v0, v116, v117
	v_mul_f32_e32 v116, 0xbfb8aa3b, v124
	v_exp_f32_e32 v118, v116
	v_mul_f32_e32 v116, 0xbfb8aa3b, v125
	v_exp_f32_e32 v119, v116
	v_mul_f32_e32 v120, 0xbfb8aa3b, v126
	v_mul_f32_e32 v121, 0xbfb8aa3b, v127
	v_add_f32_e32 v118, 1.0, v118
	v_add_f32_e32 v119, 1.0, v119
	v_exp_f32_e32 v120, v120
	v_exp_f32_e32 v121, v121
	v_add_co_u32_e32 v114, vcc, s65, v190
	v_rcp_f32_e32 v118, v118
	v_rcp_f32_e32 v119, v119
	v_addc_co_u32_e32 v115, vcc, 0, v191, vcc
	v_add_co_u32_e32 v116, vcc, s57, v190
	v_add_f32_e32 v120, 1.0, v120
	s_nop 0
	v_addc_co_u32_e32 v117, vcc, 0, v191, vcc
	v_add_f32_e32 v121, 1.0, v121
	v_rcp_f32_e32 v120, v120
	v_rcp_f32_e32 v121, v121
	global_store_dword v[116:117], v0, off offset:-4096
	v_cvt_pk_bf16_f32 v0, v118, v119
	v_mul_f32_e32 v118, 0xbfb8aa3b, v128
	v_mul_f32_e32 v119, 0xbfb8aa3b, v129
	v_exp_f32_e32 v118, v118
	v_exp_f32_e32 v119, v119
	v_mul_f32_e32 v98, 0xbfb8aa3b, v98
	v_mul_f32_e32 v99, 0xbfb8aa3b, v99
	v_exp_f32_e32 v98, v98
	v_exp_f32_e32 v99, v99
	global_store_dword v[114:115], v0, off offset:1024
	v_cvt_pk_bf16_f32 v0, v120, v121
	global_store_dword v[114:115], v0, off offset:2048
	v_add_f32_e32 v0, 1.0, v118
	v_add_f32_e32 v118, 1.0, v119
	v_mul_f32_e32 v100, 0xbfb8aa3b, v100
	v_mul_f32_e32 v101, 0xbfb8aa3b, v101
	v_rcp_f32_e32 v0, v0
	v_rcp_f32_e32 v118, v118
	v_add_f32_e32 v98, 1.0, v98
	v_add_f32_e32 v99, 1.0, v99
	v_exp_f32_e32 v100, v100
	v_exp_f32_e32 v101, v101
	v_rcp_f32_e32 v98, v98
	v_rcp_f32_e32 v99, v99
	v_cvt_pk_bf16_f32 v0, v0, v118
	v_add_f32_e32 v100, 1.0, v100
	v_add_f32_e32 v101, 1.0, v101
	v_rcp_f32_e32 v100, v100
	v_rcp_f32_e32 v101, v101
	global_store_dword v[114:115], v0, off offset:3072
	v_cvt_pk_bf16_f32 v0, v98, v99
	v_mul_f32_e32 v98, 0xbfb8aa3b, v102
	v_mul_f32_e32 v99, 0xbfb8aa3b, v103
	v_exp_f32_e32 v98, v98
	v_exp_f32_e32 v99, v99
	global_store_dword v[116:117], v0, off
	v_cvt_pk_bf16_f32 v0, v100, v101
	global_store_dword v[116:117], v0, off offset:1024
	v_add_f32_e32 v0, 1.0, v98
	v_add_f32_e32 v98, 1.0, v99
	v_mul_f32_e32 v99, 0xbfb8aa3b, v104
	v_mul_f32_e32 v100, 0xbfb8aa3b, v105
	v_rcp_f32_e32 v0, v0
	v_rcp_f32_e32 v98, v98
	v_exp_f32_e32 v99, v99
	v_exp_f32_e32 v100, v100
	v_mul_f32_e32 v101, 0xbfb8aa3b, v107
	v_cvt_pk_bf16_f32 v0, v0, v98
	v_add_f32_e32 v98, 1.0, v99
	v_add_f32_e32 v99, 1.0, v100
	v_mul_f32_e32 v100, 0xbfb8aa3b, v106
	v_exp_f32_e32 v100, v100
	v_exp_f32_e32 v101, v101
	v_rcp_f32_e32 v98, v98
	v_rcp_f32_e32 v99, v99
	v_add_f32_e32 v100, 1.0, v100
	v_add_f32_e32 v101, 1.0, v101
	v_rcp_f32_e32 v100, v100
	v_rcp_f32_e32 v101, v101
	global_store_dword v[116:117], v0, off offset:2048
	v_cvt_pk_bf16_f32 v0, v98, v99
	global_store_dword v[116:117], v0, off offset:3072
	v_cvt_pk_bf16_f32 v0, v100, v101
	v_mul_f32_e32 v100, 0xbfb8aa3b, v108
	v_exp_f32_e32 v102, v100
	v_mul_f32_e32 v100, 0xbfb8aa3b, v109
	v_exp_f32_e32 v103, v100
	v_mul_f32_e32 v104, 0xbfb8aa3b, v110
	v_mul_f32_e32 v105, 0xbfb8aa3b, v111
	s_movk_i32 s4, 0x3000
	v_add_f32_e32 v102, 1.0, v102
	v_add_f32_e32 v103, 1.0, v103
	v_exp_f32_e32 v104, v104
	v_exp_f32_e32 v105, v105
	v_add_co_u32_e32 v98, vcc, s4, v190
	v_rcp_f32_e32 v102, v102
	v_rcp_f32_e32 v103, v103
	v_addc_co_u32_e32 v99, vcc, 0, v191, vcc
	v_add_co_u32_e32 v100, vcc, s62, v190
	v_add_f32_e32 v104, 1.0, v104
	s_nop 0
	v_addc_co_u32_e32 v101, vcc, 0, v191, vcc
	v_add_f32_e32 v105, 1.0, v105
	v_rcp_f32_e32 v104, v104
	v_rcp_f32_e32 v105, v105
	global_store_dword v[100:101], v0, off offset:-4096
	v_cvt_pk_bf16_f32 v0, v102, v103
	v_mul_f32_e32 v102, 0xbfb8aa3b, v112
	v_mul_f32_e32 v103, 0xbfb8aa3b, v113
	v_exp_f32_e32 v102, v102
	v_exp_f32_e32 v103, v103
	v_mul_f32_e32 v82, 0xbfb8aa3b, v82
	v_mul_f32_e32 v83, 0xbfb8aa3b, v83
	v_exp_f32_e32 v82, v82
	v_exp_f32_e32 v83, v83
	global_store_dword v[98:99], v0, off offset:1024
	v_cvt_pk_bf16_f32 v0, v104, v105
	global_store_dword v[98:99], v0, off offset:2048
	v_add_f32_e32 v0, 1.0, v102
	v_add_f32_e32 v102, 1.0, v103
	v_mul_f32_e32 v84, 0xbfb8aa3b, v84
	v_mul_f32_e32 v85, 0xbfb8aa3b, v85
	v_rcp_f32_e32 v0, v0
	v_rcp_f32_e32 v102, v102
	v_add_f32_e32 v82, 1.0, v82
	v_add_f32_e32 v83, 1.0, v83
	v_exp_f32_e32 v84, v84
	v_exp_f32_e32 v85, v85
	v_rcp_f32_e32 v82, v82
	v_rcp_f32_e32 v83, v83
	v_cvt_pk_bf16_f32 v0, v0, v102
	v_add_f32_e32 v84, 1.0, v84
	v_add_f32_e32 v85, 1.0, v85
	v_rcp_f32_e32 v84, v84
	v_rcp_f32_e32 v85, v85
	global_store_dword v[98:99], v0, off offset:3072
	v_cvt_pk_bf16_f32 v0, v82, v83
	v_mul_f32_e32 v82, 0xbfb8aa3b, v86
	v_mul_f32_e32 v83, 0xbfb8aa3b, v87
	v_exp_f32_e32 v82, v82
	v_exp_f32_e32 v83, v83
	global_store_dword v[100:101], v0, off
	v_cvt_pk_bf16_f32 v0, v84, v85
	global_store_dword v[100:101], v0, off offset:1024
	v_add_f32_e32 v0, 1.0, v82
	v_add_f32_e32 v82, 1.0, v83
	v_mul_f32_e32 v83, 0xbfb8aa3b, v88
	v_mul_f32_e32 v84, 0xbfb8aa3b, v89
	v_rcp_f32_e32 v0, v0
	v_rcp_f32_e32 v82, v82
	v_exp_f32_e32 v83, v83
	v_exp_f32_e32 v84, v84
	v_mul_f32_e32 v85, 0xbfb8aa3b, v91
	v_cvt_pk_bf16_f32 v0, v0, v82
	v_add_f32_e32 v82, 1.0, v83
	v_add_f32_e32 v83, 1.0, v84
	v_mul_f32_e32 v84, 0xbfb8aa3b, v90
	v_exp_f32_e32 v84, v84
	v_exp_f32_e32 v85, v85
	v_rcp_f32_e32 v82, v82
	v_rcp_f32_e32 v83, v83
	v_add_f32_e32 v84, 1.0, v84
	v_add_f32_e32 v85, 1.0, v85
	v_rcp_f32_e32 v84, v84
	v_rcp_f32_e32 v85, v85
	global_store_dword v[100:101], v0, off offset:2048
	v_cvt_pk_bf16_f32 v0, v82, v83
	global_store_dword v[100:101], v0, off offset:3072
	v_cvt_pk_bf16_f32 v0, v84, v85
	v_mul_f32_e32 v84, 0xbfb8aa3b, v92
	v_exp_f32_e32 v86, v84
	v_mul_f32_e32 v84, 0xbfb8aa3b, v93
	v_exp_f32_e32 v87, v84
	v_mul_f32_e32 v88, 0xbfb8aa3b, v94
	v_mul_f32_e32 v89, 0xbfb8aa3b, v95
	v_add_f32_e32 v86, 1.0, v86
	v_add_f32_e32 v87, 1.0, v87
	v_exp_f32_e32 v88, v88
	v_exp_f32_e32 v89, v89
	v_add_co_u32_e32 v82, vcc, s64, v190
	v_rcp_f32_e32 v86, v86
	v_rcp_f32_e32 v87, v87
	v_addc_co_u32_e32 v83, vcc, 0, v191, vcc
	v_add_co_u32_e32 v84, vcc, s88, v190
	v_add_f32_e32 v88, 1.0, v88
	s_nop 0
	v_addc_co_u32_e32 v85, vcc, 0, v191, vcc
	v_add_f32_e32 v89, 1.0, v89
	v_rcp_f32_e32 v88, v88
	v_rcp_f32_e32 v89, v89
	global_store_dword v[84:85], v0, off offset:-4096
	v_cvt_pk_bf16_f32 v0, v86, v87
	v_mul_f32_e32 v86, 0xbfb8aa3b, v96
	v_mul_f32_e32 v87, 0xbfb8aa3b, v97
	v_exp_f32_e32 v86, v86
	v_exp_f32_e32 v87, v87
	v_mul_f32_e32 v66, 0xbfb8aa3b, v66
	v_mul_f32_e32 v67, 0xbfb8aa3b, v67
	v_exp_f32_e32 v66, v66
	v_exp_f32_e32 v67, v67
	global_store_dword v[82:83], v0, off offset:1024
	v_cvt_pk_bf16_f32 v0, v88, v89
	global_store_dword v[82:83], v0, off offset:2048
	v_add_f32_e32 v0, 1.0, v86
	v_add_f32_e32 v86, 1.0, v87
	v_mul_f32_e32 v68, 0xbfb8aa3b, v68
	v_mul_f32_e32 v69, 0xbfb8aa3b, v69
	v_rcp_f32_e32 v0, v0
	v_rcp_f32_e32 v86, v86
	v_add_f32_e32 v66, 1.0, v66
	v_add_f32_e32 v67, 1.0, v67
	v_exp_f32_e32 v68, v68
	v_exp_f32_e32 v69, v69
	v_rcp_f32_e32 v66, v66
	v_rcp_f32_e32 v67, v67
	v_cvt_pk_bf16_f32 v0, v0, v86
	v_add_f32_e32 v68, 1.0, v68
	v_add_f32_e32 v69, 1.0, v69
	v_rcp_f32_e32 v68, v68
	v_rcp_f32_e32 v69, v69
	global_store_dword v[82:83], v0, off offset:3072
	v_cvt_pk_bf16_f32 v0, v66, v67
	v_mul_f32_e32 v66, 0xbfb8aa3b, v70
	v_mul_f32_e32 v67, 0xbfb8aa3b, v71
	v_exp_f32_e32 v66, v66
	v_exp_f32_e32 v67, v67
	global_store_dword v[84:85], v0, off
	v_cvt_pk_bf16_f32 v0, v68, v69
	global_store_dword v[84:85], v0, off offset:1024
	v_add_f32_e32 v0, 1.0, v66
	v_add_f32_e32 v66, 1.0, v67
	v_mul_f32_e32 v67, 0xbfb8aa3b, v72
	v_mul_f32_e32 v68, 0xbfb8aa3b, v73
	v_rcp_f32_e32 v0, v0
	v_rcp_f32_e32 v66, v66
	v_exp_f32_e32 v67, v67
	v_exp_f32_e32 v68, v68
	v_mul_f32_e32 v69, 0xbfb8aa3b, v75
	v_cvt_pk_bf16_f32 v0, v0, v66
	v_add_f32_e32 v66, 1.0, v67
	v_add_f32_e32 v67, 1.0, v68
	v_mul_f32_e32 v68, 0xbfb8aa3b, v74
	v_exp_f32_e32 v68, v68
	v_exp_f32_e32 v69, v69
	v_rcp_f32_e32 v66, v66
	v_rcp_f32_e32 v67, v67
	v_add_f32_e32 v68, 1.0, v68
	v_add_f32_e32 v69, 1.0, v69
	v_rcp_f32_e32 v68, v68
	v_rcp_f32_e32 v69, v69
	global_store_dword v[84:85], v0, off offset:2048
	v_cvt_pk_bf16_f32 v0, v66, v67
	global_store_dword v[84:85], v0, off offset:3072
	v_cvt_pk_bf16_f32 v0, v68, v69
	v_mul_f32_e32 v68, 0xbfb8aa3b, v76
	v_exp_f32_e32 v70, v68
	v_mul_f32_e32 v68, 0xbfb8aa3b, v77
	v_exp_f32_e32 v71, v68
	v_mul_f32_e32 v72, 0xbfb8aa3b, v78
	v_mul_f32_e32 v73, 0xbfb8aa3b, v79
	s_movk_i32 s4, 0x7000
	v_add_f32_e32 v70, 1.0, v70
	v_add_f32_e32 v71, 1.0, v71
	v_exp_f32_e32 v72, v72
	v_exp_f32_e32 v73, v73
	v_add_co_u32_e32 v66, vcc, s4, v190
	v_rcp_f32_e32 v70, v70
	v_rcp_f32_e32 v71, v71
	v_addc_co_u32_e32 v67, vcc, 0, v191, vcc
	s_mov_b32 s4, 0x8000
	v_add_co_u32_e32 v68, vcc, s4, v190
	v_add_f32_e32 v72, 1.0, v72
	s_nop 0
	v_addc_co_u32_e32 v69, vcc, 0, v191, vcc
	v_add_f32_e32 v73, 1.0, v73
	v_rcp_f32_e32 v72, v72
	v_rcp_f32_e32 v73, v73
	global_store_dword v[68:69], v0, off offset:-4096
	v_cvt_pk_bf16_f32 v0, v70, v71
	v_mul_f32_e32 v70, 0xbfb8aa3b, v80
	v_mul_f32_e32 v71, 0xbfb8aa3b, v81
	v_exp_f32_e32 v70, v70
	v_exp_f32_e32 v71, v71
	v_mul_f32_e32 v50, 0xbfb8aa3b, v50
	v_mul_f32_e32 v51, 0xbfb8aa3b, v51
	v_exp_f32_e32 v50, v50
	v_exp_f32_e32 v51, v51
	global_store_dword v[66:67], v0, off offset:1024
	v_cvt_pk_bf16_f32 v0, v72, v73
	global_store_dword v[66:67], v0, off offset:2048
	v_add_f32_e32 v0, 1.0, v70
	v_add_f32_e32 v70, 1.0, v71
	v_mul_f32_e32 v52, 0xbfb8aa3b, v52
	v_mul_f32_e32 v53, 0xbfb8aa3b, v53
	v_rcp_f32_e32 v0, v0
	v_rcp_f32_e32 v70, v70
	v_add_f32_e32 v50, 1.0, v50
	v_add_f32_e32 v51, 1.0, v51
	v_exp_f32_e32 v52, v52
	v_exp_f32_e32 v53, v53
	v_rcp_f32_e32 v50, v50
	v_rcp_f32_e32 v51, v51
	v_cvt_pk_bf16_f32 v0, v0, v70
	v_add_f32_e32 v52, 1.0, v52
	v_add_f32_e32 v53, 1.0, v53
	v_rcp_f32_e32 v52, v52
	v_rcp_f32_e32 v53, v53
	global_store_dword v[66:67], v0, off offset:3072
	v_cvt_pk_bf16_f32 v0, v50, v51
	v_mul_f32_e32 v50, 0xbfb8aa3b, v54
	v_mul_f32_e32 v51, 0xbfb8aa3b, v55
	v_exp_f32_e32 v50, v50
	v_exp_f32_e32 v51, v51
	global_store_dword v[68:69], v0, off
	v_cvt_pk_bf16_f32 v0, v52, v53
	global_store_dword v[68:69], v0, off offset:1024
	v_add_f32_e32 v0, 1.0, v50
	v_add_f32_e32 v50, 1.0, v51
	v_mul_f32_e32 v51, 0xbfb8aa3b, v56
	v_mul_f32_e32 v52, 0xbfb8aa3b, v57
	v_rcp_f32_e32 v0, v0
	v_rcp_f32_e32 v50, v50
	v_exp_f32_e32 v51, v51
	v_exp_f32_e32 v52, v52
	v_mul_f32_e32 v53, 0xbfb8aa3b, v59
	v_cvt_pk_bf16_f32 v0, v0, v50
	v_add_f32_e32 v50, 1.0, v51
	v_add_f32_e32 v51, 1.0, v52
	v_mul_f32_e32 v52, 0xbfb8aa3b, v58
	v_exp_f32_e32 v52, v52
	v_exp_f32_e32 v53, v53
	v_rcp_f32_e32 v50, v50
	v_rcp_f32_e32 v51, v51
	v_add_f32_e32 v52, 1.0, v52
	v_add_f32_e32 v53, 1.0, v53
	v_rcp_f32_e32 v52, v52
	v_rcp_f32_e32 v53, v53
	global_store_dword v[68:69], v0, off offset:2048
	v_cvt_pk_bf16_f32 v0, v50, v51
	global_store_dword v[68:69], v0, off offset:3072
	v_cvt_pk_bf16_f32 v0, v52, v53
	v_mul_f32_e32 v52, 0xbfb8aa3b, v60
	v_exp_f32_e32 v54, v52
	v_mul_f32_e32 v52, 0xbfb8aa3b, v61
	v_exp_f32_e32 v55, v52
	v_mul_f32_e32 v56, 0xbfb8aa3b, v62
	v_mul_f32_e32 v57, 0xbfb8aa3b, v63
	s_mov_b32 s4, 0x9000
	v_add_f32_e32 v54, 1.0, v54
	v_add_f32_e32 v55, 1.0, v55
	v_exp_f32_e32 v56, v56
	v_exp_f32_e32 v57, v57
	v_add_co_u32_e32 v50, vcc, s4, v190
	v_rcp_f32_e32 v54, v54
	v_rcp_f32_e32 v55, v55
	v_addc_co_u32_e32 v51, vcc, 0, v191, vcc
	s_mov_b32 s4, 0xa000
	v_add_co_u32_e32 v52, vcc, s4, v190
	v_add_f32_e32 v56, 1.0, v56
	s_nop 0
	v_addc_co_u32_e32 v53, vcc, 0, v191, vcc
	v_add_f32_e32 v57, 1.0, v57
	v_rcp_f32_e32 v56, v56
	v_rcp_f32_e32 v57, v57
	global_store_dword v[52:53], v0, off offset:-4096
	v_cvt_pk_bf16_f32 v0, v54, v55
	v_mul_f32_e32 v54, 0xbfb8aa3b, v64
	v_mul_f32_e32 v55, 0xbfb8aa3b, v65
	v_exp_f32_e32 v54, v54
	v_exp_f32_e32 v55, v55
	v_mul_f32_e32 v34, 0xbfb8aa3b, v34
	v_mul_f32_e32 v35, 0xbfb8aa3b, v35
	v_exp_f32_e32 v34, v34
	v_exp_f32_e32 v35, v35
	global_store_dword v[50:51], v0, off offset:1024
	v_cvt_pk_bf16_f32 v0, v56, v57
	global_store_dword v[50:51], v0, off offset:2048
	v_add_f32_e32 v0, 1.0, v54
	v_add_f32_e32 v54, 1.0, v55
	v_mul_f32_e32 v36, 0xbfb8aa3b, v36
	v_mul_f32_e32 v37, 0xbfb8aa3b, v37
	v_rcp_f32_e32 v0, v0
	v_rcp_f32_e32 v54, v54
	v_add_f32_e32 v34, 1.0, v34
	v_add_f32_e32 v35, 1.0, v35
	v_exp_f32_e32 v36, v36
	v_exp_f32_e32 v37, v37
	v_rcp_f32_e32 v34, v34
	v_rcp_f32_e32 v35, v35
	v_cvt_pk_bf16_f32 v0, v0, v54
	v_add_f32_e32 v36, 1.0, v36
	v_add_f32_e32 v37, 1.0, v37
	v_rcp_f32_e32 v36, v36
	v_rcp_f32_e32 v37, v37
	global_store_dword v[50:51], v0, off offset:3072
	v_cvt_pk_bf16_f32 v0, v34, v35
	v_mul_f32_e32 v34, 0xbfb8aa3b, v38
	v_mul_f32_e32 v35, 0xbfb8aa3b, v39
	v_exp_f32_e32 v34, v34
	v_exp_f32_e32 v35, v35
	global_store_dword v[52:53], v0, off
	v_cvt_pk_bf16_f32 v0, v36, v37
	global_store_dword v[52:53], v0, off offset:1024
	v_add_f32_e32 v0, 1.0, v34
	v_add_f32_e32 v34, 1.0, v35
	v_mul_f32_e32 v35, 0xbfb8aa3b, v40
	v_mul_f32_e32 v36, 0xbfb8aa3b, v41
	v_rcp_f32_e32 v0, v0
	v_rcp_f32_e32 v34, v34
	v_exp_f32_e32 v35, v35
	v_exp_f32_e32 v36, v36
	v_mul_f32_e32 v37, 0xbfb8aa3b, v43
	v_cvt_pk_bf16_f32 v0, v0, v34
	v_add_f32_e32 v34, 1.0, v35
	v_add_f32_e32 v35, 1.0, v36
	v_mul_f32_e32 v36, 0xbfb8aa3b, v42
	v_exp_f32_e32 v36, v36
	v_exp_f32_e32 v37, v37
	v_rcp_f32_e32 v34, v34
	v_rcp_f32_e32 v35, v35
	v_add_f32_e32 v36, 1.0, v36
	v_add_f32_e32 v37, 1.0, v37
	v_rcp_f32_e32 v36, v36
	v_rcp_f32_e32 v37, v37
	global_store_dword v[52:53], v0, off offset:2048
	v_cvt_pk_bf16_f32 v0, v34, v35
	global_store_dword v[52:53], v0, off offset:3072
	v_cvt_pk_bf16_f32 v0, v36, v37
	v_mul_f32_e32 v36, 0xbfb8aa3b, v44
	v_exp_f32_e32 v38, v36
	v_mul_f32_e32 v36, 0xbfb8aa3b, v45
	v_exp_f32_e32 v39, v36
	v_mul_f32_e32 v40, 0xbfb8aa3b, v46
	v_mul_f32_e32 v41, 0xbfb8aa3b, v47
	s_mov_b32 s4, 0xb000
	v_add_f32_e32 v38, 1.0, v38
	v_add_f32_e32 v39, 1.0, v39
	v_exp_f32_e32 v40, v40
	v_exp_f32_e32 v41, v41
	v_add_co_u32_e32 v34, vcc, s4, v190
	v_rcp_f32_e32 v38, v38
	v_rcp_f32_e32 v39, v39
	v_addc_co_u32_e32 v35, vcc, 0, v191, vcc
	s_mov_b32 s4, 0xc000
	v_add_co_u32_e32 v36, vcc, s4, v190
	v_add_f32_e32 v40, 1.0, v40
	s_nop 0
	v_addc_co_u32_e32 v37, vcc, 0, v191, vcc
	v_add_f32_e32 v41, 1.0, v41
	v_rcp_f32_e32 v40, v40
	v_rcp_f32_e32 v41, v41
	global_store_dword v[36:37], v0, off offset:-4096
	v_cvt_pk_bf16_f32 v0, v38, v39
	v_mul_f32_e32 v38, 0xbfb8aa3b, v48
	v_mul_f32_e32 v39, 0xbfb8aa3b, v49
	v_exp_f32_e32 v38, v38
	v_exp_f32_e32 v39, v39
	v_mul_f32_e32 v18, 0xbfb8aa3b, v18
	v_mul_f32_e32 v19, 0xbfb8aa3b, v19
	v_exp_f32_e32 v18, v18
	v_exp_f32_e32 v19, v19
	global_store_dword v[34:35], v0, off offset:1024
	v_cvt_pk_bf16_f32 v0, v40, v41
	global_store_dword v[34:35], v0, off offset:2048
	v_add_f32_e32 v0, 1.0, v38
	v_add_f32_e32 v38, 1.0, v39
	v_mul_f32_e32 v20, 0xbfb8aa3b, v20
	v_mul_f32_e32 v21, 0xbfb8aa3b, v21
	v_rcp_f32_e32 v0, v0
	v_rcp_f32_e32 v38, v38
	v_add_f32_e32 v18, 1.0, v18
	v_add_f32_e32 v19, 1.0, v19
	v_exp_f32_e32 v20, v20
	v_exp_f32_e32 v21, v21
	v_rcp_f32_e32 v18, v18
	v_rcp_f32_e32 v19, v19
	v_cvt_pk_bf16_f32 v0, v0, v38
	v_add_f32_e32 v20, 1.0, v20
	v_add_f32_e32 v21, 1.0, v21
	v_rcp_f32_e32 v20, v20
	v_rcp_f32_e32 v21, v21
	global_store_dword v[34:35], v0, off offset:3072
	v_cvt_pk_bf16_f32 v0, v18, v19
	v_mul_f32_e32 v18, 0xbfb8aa3b, v22
	v_mul_f32_e32 v19, 0xbfb8aa3b, v23
	v_exp_f32_e32 v18, v18
	v_exp_f32_e32 v19, v19
	global_store_dword v[36:37], v0, off
	v_cvt_pk_bf16_f32 v0, v20, v21
	global_store_dword v[36:37], v0, off offset:1024
	v_add_f32_e32 v0, 1.0, v18
	v_add_f32_e32 v18, 1.0, v19
	v_mul_f32_e32 v19, 0xbfb8aa3b, v24
	v_mul_f32_e32 v20, 0xbfb8aa3b, v25
	v_rcp_f32_e32 v0, v0
	v_rcp_f32_e32 v18, v18
	v_exp_f32_e32 v19, v19
	v_exp_f32_e32 v20, v20
	v_mul_f32_e32 v21, 0xbfb8aa3b, v27
	v_cvt_pk_bf16_f32 v0, v0, v18
	v_add_f32_e32 v18, 1.0, v19
	v_add_f32_e32 v19, 1.0, v20
	v_mul_f32_e32 v20, 0xbfb8aa3b, v26
	v_exp_f32_e32 v20, v20
	v_exp_f32_e32 v21, v21
	v_rcp_f32_e32 v18, v18
	v_rcp_f32_e32 v19, v19
	v_add_f32_e32 v20, 1.0, v20
	v_add_f32_e32 v21, 1.0, v21
	v_rcp_f32_e32 v20, v20
	v_rcp_f32_e32 v21, v21
	global_store_dword v[36:37], v0, off offset:2048
	v_cvt_pk_bf16_f32 v0, v18, v19
	global_store_dword v[36:37], v0, off offset:3072
	v_cvt_pk_bf16_f32 v0, v20, v21
	v_mul_f32_e32 v20, 0xbfb8aa3b, v28
	v_exp_f32_e32 v22, v20
	v_mul_f32_e32 v20, 0xbfb8aa3b, v29
	v_exp_f32_e32 v23, v20
	v_mul_f32_e32 v24, 0xbfb8aa3b, v30
	v_mul_f32_e32 v25, 0xbfb8aa3b, v31
	s_mov_b32 s4, 0xd000
	v_add_f32_e32 v22, 1.0, v22
	v_add_f32_e32 v23, 1.0, v23
	v_exp_f32_e32 v24, v24
	v_exp_f32_e32 v25, v25
	v_add_co_u32_e32 v18, vcc, s4, v190
	v_rcp_f32_e32 v22, v22
	v_rcp_f32_e32 v23, v23
	v_addc_co_u32_e32 v19, vcc, 0, v191, vcc
	s_mov_b32 s4, 0xe000
	v_add_co_u32_e32 v20, vcc, s4, v190
	v_add_f32_e32 v24, 1.0, v24
	s_nop 0
	v_addc_co_u32_e32 v21, vcc, 0, v191, vcc
	v_add_f32_e32 v25, 1.0, v25
	v_rcp_f32_e32 v24, v24
	v_rcp_f32_e32 v25, v25
	global_store_dword v[20:21], v0, off offset:-4096
	v_cvt_pk_bf16_f32 v0, v22, v23
	v_mul_f32_e32 v22, 0xbfb8aa3b, v32
	v_mul_f32_e32 v23, 0xbfb8aa3b, v33
	v_exp_f32_e32 v22, v22
	v_exp_f32_e32 v23, v23
	v_mul_f32_e32 v2, 0xbfb8aa3b, v2
	v_mul_f32_e32 v3, 0xbfb8aa3b, v3
	v_exp_f32_e32 v2, v2
	v_exp_f32_e32 v3, v3
	global_store_dword v[18:19], v0, off offset:1024
	v_cvt_pk_bf16_f32 v0, v24, v25
	global_store_dword v[18:19], v0, off offset:2048
	v_add_f32_e32 v0, 1.0, v22
	v_add_f32_e32 v22, 1.0, v23
	v_mul_f32_e32 v4, 0xbfb8aa3b, v4
	v_mul_f32_e32 v5, 0xbfb8aa3b, v5
	v_rcp_f32_e32 v0, v0
	v_rcp_f32_e32 v22, v22
	v_add_f32_e32 v2, 1.0, v2
	v_add_f32_e32 v3, 1.0, v3
	v_exp_f32_e32 v4, v4
	v_exp_f32_e32 v5, v5
	v_rcp_f32_e32 v2, v2
	v_rcp_f32_e32 v3, v3
	v_cvt_pk_bf16_f32 v0, v0, v22
	v_add_f32_e32 v4, 1.0, v4
	v_add_f32_e32 v5, 1.0, v5
	v_rcp_f32_e32 v4, v4
	v_rcp_f32_e32 v5, v5
	global_store_dword v[18:19], v0, off offset:3072
	v_cvt_pk_bf16_f32 v0, v2, v3
	v_mul_f32_e32 v2, 0xbfb8aa3b, v6
	v_mul_f32_e32 v3, 0xbfb8aa3b, v7
	v_exp_f32_e32 v2, v2
	v_exp_f32_e32 v3, v3
	global_store_dword v[20:21], v0, off
	v_cvt_pk_bf16_f32 v0, v4, v5
	global_store_dword v[20:21], v0, off offset:1024
	v_add_f32_e32 v0, 1.0, v2
	v_add_f32_e32 v2, 1.0, v3
	v_mul_f32_e32 v3, 0xbfb8aa3b, v8
	v_mul_f32_e32 v4, 0xbfb8aa3b, v9
	v_rcp_f32_e32 v0, v0
	v_rcp_f32_e32 v2, v2
	v_exp_f32_e32 v3, v3
	v_exp_f32_e32 v4, v4
	v_mul_f32_e32 v5, 0xbfb8aa3b, v11
	v_cvt_pk_bf16_f32 v0, v0, v2
	v_add_f32_e32 v2, 1.0, v3
	v_add_f32_e32 v3, 1.0, v4
	v_mul_f32_e32 v4, 0xbfb8aa3b, v10
	v_exp_f32_e32 v4, v4
	v_exp_f32_e32 v5, v5
	v_rcp_f32_e32 v2, v2
	v_rcp_f32_e32 v3, v3
	v_add_f32_e32 v4, 1.0, v4
	v_add_f32_e32 v5, 1.0, v5
	v_rcp_f32_e32 v4, v4
	v_rcp_f32_e32 v5, v5
	global_store_dword v[20:21], v0, off offset:2048
	v_cvt_pk_bf16_f32 v0, v2, v3
	global_store_dword v[20:21], v0, off offset:3072
	v_cvt_pk_bf16_f32 v0, v4, v5
	v_mul_f32_e32 v4, 0xbfb8aa3b, v12
	v_mul_f32_e32 v5, 0xbfb8aa3b, v13
	v_exp_f32_e32 v4, v4
	v_exp_f32_e32 v5, v5
	s_mov_b32 s4, 0xf000
	v_add_co_u32_e32 v2, vcc, s4, v190
	v_mul_f32_e32 v6, 0xbfb8aa3b, v15
	s_nop 0
	v_addc_co_u32_e32 v3, vcc, 0, v191, vcc
	global_store_dword v[2:3], v0, off
	v_add_f32_e32 v0, 1.0, v4
	v_add_f32_e32 v4, 1.0, v5
	v_mul_f32_e32 v5, 0xbfb8aa3b, v14
	v_rcp_f32_e32 v0, v0
	v_rcp_f32_e32 v4, v4
	v_exp_f32_e32 v5, v5
	v_exp_f32_e32 v6, v6
	v_mul_f32_e32 v7, 0xbfb8aa3b, v17
	v_cvt_pk_bf16_f32 v0, v0, v4
	v_add_f32_e32 v4, 1.0, v5
	v_add_f32_e32 v5, 1.0, v6
	v_mul_f32_e32 v6, 0xbfb8aa3b, v16
	v_exp_f32_e32 v6, v6
	v_exp_f32_e32 v7, v7
	v_rcp_f32_e32 v4, v4
	v_rcp_f32_e32 v5, v5
	v_add_f32_e32 v6, 1.0, v6
	v_add_f32_e32 v7, 1.0, v7
	v_rcp_f32_e32 v6, v6
	v_rcp_f32_e32 v7, v7
	global_store_dword v[2:3], v0, off offset:1024
	v_cvt_pk_bf16_f32 v0, v4, v5
	global_store_dword v[2:3], v0, off offset:2048
	v_cvt_pk_bf16_f32 v0, v6, v7
	s_mov_b32 s9, 8
	global_store_dword v[2:3], v0, off offset:3072
	s_branch .LBB0_77
